# v14 + rwkv loop unrolled by chunk parity with two global-prefetch register sets (loads issued at chunk start, consumed 1.4 chunks later)
# speedup vs baseline: 1.0244x; 1.0010x over previous
; __device__ __forceinline__ float lo2f(unsigned w) { return __uint_as_float(w << 16); }
; __device__ __forceinline__ float hi2f(unsigned w) { return __uint_as_float(w & 0xffff0000u); }
; __device__ __forceinline__ void rwkv_scan_unit(CP p, int u, char* smem) {
;     ...
;   auto gload = [&](int c) {
;     const int rb = rowof(b, c * 16);
; #pragma unroll
;     for (int x = 0; x < 3; ++x) {
;       const int e = tid + x * 256, tok = e / 48, rem = e % 48, vec = rem >> 3, part = rem & 7;
;       st[x] = *reinterpret_cast<const uint4*>(RW + (size_t)(rb + tok) * 1536 + vec * 256 + h * 64 + part * 8);
;     }
;   };
;   auto lwrite = [&](int bi) {
; #pragma unroll
;     for (int x = 0; x < 3; ++x) {
;       const int e = tid + x * 256, tok = e / 48, rem = e % 48, vec = rem >> 3, part = rem & 7;
;       float* d = buf + bi * 6144 + tok * 384 + vec * 64 + part * 8;
;       *reinterpret_cast<float4*>(d) = make_float4(lo2f(st[x].x), hi2f(st[x].x), lo2f(st[x].y), hi2f(st[x].y));
;       *reinterpret_cast<float4*>(d + 4) = make_float4(lo2f(st[x].z), hi2f(st[x].z), lo2f(st[x].w), hi2f(st[x].w));
;     }
;   };
;   half_barrier(smem);
;   gload(0);
;   lwrite(0);
;   half_barrier(smem);
;   constexpr int NCH = T / 16;
;   for (int c = 0; c < NCH; ++c) {
;     if (c + 1 < NCH) gload(c + 1);
;     const float* cb = buf + (c & 1) * 6144;
;     float ykeep = 0.f;
;     float4 om = *reinterpret_cast<const float4*>(cb + j * 4);
;     float4 kk = *reinterpret_cast<const float4*>(cb + 64 + j * 4);
;     float4 bb = *reinterpret_cast<const float4*>(cb + 128 + j * 4);
;     float4 kp = *reinterpret_cast<const float4*>(cb + 192 + j * 4);
;     float4 rr = *reinterpret_cast<const float4*>(cb + 256 + j * 4);
;     float vv = cb[320 + rowv];
; #pragma unroll 2
;     for (int s = 0; s < 16; ++s) {
;       const float* sb = cb + (s + 1) * 384;
;       const float4 om_n = *reinterpret_cast<const float4*>(sb + j * 4);
;       const float4 kk_n = *reinterpret_cast<const float4*>(sb + 64 + j * 4);
;       const float4 bb_n = *reinterpret_cast<const float4*>(sb + 128 + j * 4);
;       const float4 kp_n = *reinterpret_cast<const float4*>(sb + 192 + j * 4);
;       const float4 rr_n = *reinterpret_cast<const float4*>(sb + 256 + j * 4);
;       const float vv_n = sb[320 + rowv];
.LBB0_572:
	s_or_b64 exec, exec, s[2:3]
	s_and_b32 s12, s11, 48
	v_readlane_b32 s0, v254, 1
	v_readlane_b32 s1, v254, 2
	s_add_u32 s2, s0, s80
	s_addc_u32 s3, s1, 0
	s_lshl_b32 s4, s57, 7
	v_ashrrev_i32_e32 v17, 4, v22
	s_and_b32 s11, s4, 0xfffff800
	v_bfe_u32 v23, v22, 4, 2
	v_and_b32_e32 v76, 15, v22
	v_and_b32_e32 v22, -4, v17
	s_add_i32 s11, s11, -16
	v_add_u32_e32 v17, s12, v22
	v_lshl_add_u64 v[12:13], v[12:13], 1, s[2:3]
	s_add_u32 s4, s30, s80
	v_or_b32_e32 v48, v17, v23
	v_lshl_add_u64 v[50:51], v[12:13], 0, v[148:149]
	v_lshl_add_u64 v[12:13], v[14:15], 1, s[2:3]
	v_mov_b32_e32 v17, v149
	s_addc_u32 s5, s31, 0
	s_and_b32 s12, s37, 48
	v_lshl_add_u64 v[52:53], v[12:13], 0, v[16:17]
	v_lshl_add_u64 v[12:13], v[18:19], 1, s[2:3]
	v_mov_b32_e32 v21, v149
	v_lshl_add_u64 v[54:55], v[12:13], 0, v[20:21]
	v_add_u32_e32 v12, s12, v22
	v_ashrrev_i32_e32 v49, 31, v48
	v_or_b32_e32 v12, v12, v23
	v_mov_b32_e32 v148, v149
	v_lshlrev_b32_e32 v77, 2, v76
	v_lshl_add_u64 v[56:57], v[48:49], 1, s[4:5]
	v_lshl_add_u32 v49, v12, 2, s36
	v_lshl_add_u32 v78, v76, 4, s56
	s_mov_b32 s4, 0
	v_mov_b64_e32 v[60:61], v[148:149]
	v_mov_b64_e32 v[58:59], v[148:149]
	v_mov_b32_e32 v193, 0x20000
	v_lshl_add_u32 v193, v213, 2, v193
	v_mov_b32_e32 v195, 1
	ds_read_b32 v194, v193 offset:8
	s_add_i32 s5, s11, 16
	v_add_u32_e32 v198, s5, v63
	v_add_u32_e32 v202, s5, v65
	v_add_u32_e32 v206, s5, v66
	v_mad_i64_i32 v[198:199], s[12:13], v198, s66, v[50:51]
	v_mad_i64_i32 v[202:203], s[12:13], v202, s66, v[52:53]
	v_mad_i64_i32 v[206:207], s[12:13], v206, s66, v[54:55]
	global_load_dwordx4 v[198:201], v[198:199], off
	global_load_dwordx4 v[202:205], v[202:203], off
	global_load_dwordx4 v[206:209], v[206:207], off
	s_waitcnt lgkmcnt(0)
	v_and_b32_e32 v194, -4, v194
.Lrw_headE:
	s_add_i32 s28, s4, 1
	s_mov_b32 s13, s63
	v_lshl_add_u32 v78, v77, 2, s13
	v_lshl_add_u32 v79, v48, 2, s13
	s_cmpk_gt_i32 s4, 0x7e
	s_cbranch_scc0 .Lrw_doglE
	s_waitcnt vmcnt(0)
	s_branch .Lrw_skipglE
.Lrw_doglE:
	s_add_i32 s5, s4, 2
	s_lshl_b32 s5, s5, 4
	s_add_i32 s5, s5, s11
	v_add_u32_e32 v0, s5, v63
	v_add_u32_e32 v4, s5, v65
	v_add_u32_e32 v8, s5, v66
	v_mad_i64_i32 v[0:1], s[12:13], v0, s66, v[50:51]
	v_mad_i64_i32 v[4:5], s[12:13], v4, s66, v[52:53]
	v_mad_i64_i32 v[8:9], s[12:13], v8, s66, v[54:55]
	global_load_dwordx4 v[0:3], v[0:1], off
	global_load_dwordx4 v[4:7], v[4:5], off
	global_load_dwordx4 v[8:11], v[8:9], off
.Lrw_skipglE:
	ds_read_b128 v[94:97], v78 offset:256
	ds_read_b128 v[90:93], v78 offset:0
	ds_read_b128 v[102:105], v78 offset:768
	ds_read_b32 v110, v79 offset:1280
	ds_read_b128 v[98:101], v78 offset:512
	ds_read_b128 v[106:109], v78 offset:1024
	ds_read_b128 v[116:119], v78 offset:1792
	ds_read_b128 v[112:115], v78 offset:1536
	ds_read_b128 v[124:127], v78 offset:2304
	ds_read_b32 v132, v79 offset:2816
	ds_read_b128 v[120:123], v78 offset:2048
	ds_read_b128 v[128:131], v78 offset:2560
	s_waitcnt lgkmcnt(7)
	v_pk_mul_f32 v[176:177], v[60:61], v[94:95]
	v_pk_fma_f32 v[176:177], v[58:59], v[96:97], v[176:177]
	ds_read_b128 v[138:141], v78 offset:3328
	ds_read_b128 v[134:137], v78 offset:3072
	v_pk_fma_f32 v[180:181], v[60:61], v[90:91], v[60:61] neg_lo:[1,0,0] neg_hi:[1,0,0]
	v_add_f32_e32 v178, v176, v177
	v_pk_fma_f32 v[182:183], v[58:59], v[92:93], v[58:59] neg_lo:[1,0,0] neg_hi:[1,0,0]
	ds_read_b128 v[152:155], v78 offset:3840
	v_add_f32_dpp v178, v178, v178 quad_perm:[1,0,3,2] row_mask:0xf bank_mask:0xf bound_ctrl:1
	v_pk_fma_f32 v[180:181], v[110:111], v[102:103], v[180:181] op_sel_hi:[0,1,1]
	v_pk_fma_f32 v[182:183], v[110:111], v[104:105], v[182:183] op_sel_hi:[0,1,1]
	v_add_f32_dpp v178, v178, v178 quad_perm:[2,3,0,1] row_mask:0xf bank_mask:0xf bound_ctrl:1
	ds_read_b32 v146, v79 offset:4352
	ds_read_b128 v[142:145], v78 offset:3584
	v_add_f32_dpp v178, v178, v178 row_half_mirror row_mask:0xf bank_mask:0xf bound_ctrl:1
	ds_read_b128 v[156:159], v78 offset:4096
	s_nop 0
	v_add_f32_dpp v178, v178, v178 row_mirror row_mask:0xf bank_mask:0xf bound_ctrl:1
	v_pk_fma_f32 v[60:61], v[178:179], v[98:99], v[180:181] op_sel_hi:[0,1,1] neg_lo:[1,0,0] neg_hi:[1,0,0]
	v_pk_fma_f32 v[58:59], v[178:179], v[100:101], v[182:183] op_sel_hi:[0,1,1] neg_lo:[1,0,0] neg_hi:[1,0,0]
	s_waitcnt lgkmcnt(7)
	v_pk_mul_f32 v[176:177], v[60:61], v[116:117]
	v_pk_fma_f32 v[176:177], v[58:59], v[118:119], v[176:177]
	ds_read_b128 v[94:97], v78 offset:4864
	ds_read_b128 v[90:93], v78 offset:4608
	v_pk_fma_f32 v[180:181], v[60:61], v[112:113], v[60:61] neg_lo:[1,0,0] neg_hi:[1,0,0]
	v_add_f32_e32 v178, v176, v177
	v_pk_fma_f32 v[182:183], v[58:59], v[114:115], v[58:59] neg_lo:[1,0,0] neg_hi:[1,0,0]
	ds_read_b128 v[102:105], v78 offset:5376
	v_add_f32_dpp v178, v178, v178 quad_perm:[1,0,3,2] row_mask:0xf bank_mask:0xf bound_ctrl:1
	v_pk_fma_f32 v[180:181], v[132:133], v[124:125], v[180:181] op_sel_hi:[0,1,1]
	v_pk_fma_f32 v[182:183], v[132:133], v[126:127], v[182:183] op_sel_hi:[0,1,1]
	v_add_f32_dpp v178, v178, v178 quad_perm:[2,3,0,1] row_mask:0xf bank_mask:0xf bound_ctrl:1
	v_pk_mul_f32 v[184:185], v[60:61], v[106:107]
	v_pk_fma_f32 v[184:185], v[58:59], v[108:109], v[184:185]
	v_add_f32_dpp v178, v178, v178 row_half_mirror row_mask:0xf bank_mask:0xf bound_ctrl:1
	v_add_f32_e32 v160, v184, v185
	ds_read_b32 v110, v79 offset:5888
	v_add_f32_dpp v178, v178, v178 row_mirror row_mask:0xf bank_mask:0xf bound_ctrl:1
	ds_read_b128 v[98:101], v78 offset:5120
	ds_read_b128 v[106:109], v78 offset:5632
	v_pk_fma_f32 v[60:61], v[178:179], v[120:121], v[180:181] op_sel_hi:[0,1,1] neg_lo:[1,0,0] neg_hi:[1,0,0]
	v_pk_fma_f32 v[58:59], v[178:179], v[122:123], v[182:183] op_sel_hi:[0,1,1] neg_lo:[1,0,0] neg_hi:[1,0,0]
	s_waitcnt lgkmcnt(7)
; __device__ __forceinline__ void rwkv_scan_unit(CP p, int u, char* smem) {
;     ...
;     for (int s = 0; s < 16; ++s) {
;       const float* sb = cb + (s + 1) * 384;
;       const float4 om_n = *reinterpret_cast<const float4*>(sb + j * 4);
;       const float4 kk_n = *reinterpret_cast<const float4*>(sb + 64 + j * 4);
;       const float4 bb_n = *reinterpret_cast<const float4*>(sb + 128 + j * 4);
;       const float4 kp_n = *reinterpret_cast<const float4*>(sb + 192 + j * 4);
;       const float4 rr_n = *reinterpret_cast<const float4*>(sb + 256 + j * 4);
;       const float vv_n = sb[320 + rowv];
;       __builtin_amdgcn_sched_barrier(0);
;       float d = s0 * kk.x + s1 * kk.y + s2 * kk.z + s3 * kk.w;
;       d = allreduce16(d);
;       const float sa = -d;
;       s0 = fmaf(-s0, om.x, s0); s1 = fmaf(-s1, om.y, s1); s2 = fmaf(-s2, om.z, s2); s3 = fmaf(-s3, om.w, s3);
;       s0 = fmaf(sa, bb.x, s0); s1 = fmaf(sa, bb.y, s1); s2 = fmaf(sa, bb.z, s2); s3 = fmaf(sa, bb.w, s3);
;       s0 = fmaf(vv, kp.x, s0); s1 = fmaf(vv, kp.y, s1); s2 = fmaf(vv, kp.z, s2); s3 = fmaf(vv, kp.w, s3);
;       float y = s0 * rr.x + s1 * rr.y + s2 * rr.z + s3 * rr.w;
;       y = allreduce16(y);
;       if (j == s) ykeep = y;
;       om = om_n; kk = kk_n; bb = bb_n; kp = kp_n; rr = rr_n; vv = vv_n;
;     }
	v_pk_mul_f32 v[176:177], v[60:61], v[138:139]
	v_pk_fma_f32 v[176:177], v[58:59], v[140:141], v[176:177]
	ds_read_b128 v[116:119], v78 offset:6400
	ds_read_b128 v[112:115], v78 offset:6144
	v_pk_fma_f32 v[180:181], v[60:61], v[134:135], v[60:61] neg_lo:[1,0,0] neg_hi:[1,0,0]
	v_add_f32_e32 v178, v176, v177
	v_pk_fma_f32 v[182:183], v[58:59], v[136:137], v[58:59] neg_lo:[1,0,0] neg_hi:[1,0,0]
	ds_read_b128 v[124:127], v78 offset:6912
	v_add_f32_dpp v178, v178, v178 quad_perm:[1,0,3,2] row_mask:0xf bank_mask:0xf bound_ctrl:1
	v_pk_fma_f32 v[180:181], v[146:147], v[152:153], v[180:181] op_sel_hi:[0,1,1]
	v_pk_fma_f32 v[182:183], v[146:147], v[154:155], v[182:183] op_sel_hi:[0,1,1]
	v_add_f32_dpp v178, v178, v178 quad_perm:[2,3,0,1] row_mask:0xf bank_mask:0xf bound_ctrl:1
	v_pk_mul_f32 v[184:185], v[60:61], v[128:129]
	v_pk_fma_f32 v[184:185], v[58:59], v[130:131], v[184:185]
	v_add_f32_dpp v178, v178, v178 row_half_mirror row_mask:0xf bank_mask:0xf bound_ctrl:1
	v_add_f32_e32 v161, v184, v185
	ds_read_b32 v132, v79 offset:7424
	v_add_f32_dpp v178, v178, v178 row_mirror row_mask:0xf bank_mask:0xf bound_ctrl:1
	ds_read_b128 v[120:123], v78 offset:6656
	ds_read_b128 v[128:131], v78 offset:7168
	v_pk_fma_f32 v[60:61], v[178:179], v[142:143], v[180:181] op_sel_hi:[0,1,1] neg_lo:[1,0,0] neg_hi:[1,0,0]
	v_pk_fma_f32 v[58:59], v[178:179], v[144:145], v[182:183] op_sel_hi:[0,1,1] neg_lo:[1,0,0] neg_hi:[1,0,0]
	s_waitcnt lgkmcnt(7)
	v_pk_mul_f32 v[176:177], v[60:61], v[94:95]
	v_pk_fma_f32 v[176:177], v[58:59], v[96:97], v[176:177]
	ds_read_b128 v[138:141], v78 offset:7936
	ds_read_b128 v[134:137], v78 offset:7680
	v_pk_fma_f32 v[180:181], v[60:61], v[90:91], v[60:61] neg_lo:[1,0,0] neg_hi:[1,0,0]
	v_add_f32_e32 v178, v176, v177
	v_pk_fma_f32 v[182:183], v[58:59], v[92:93], v[58:59] neg_lo:[1,0,0] neg_hi:[1,0,0]
	ds_read_b128 v[152:155], v78 offset:8448
	v_add_f32_dpp v178, v178, v178 quad_perm:[1,0,3,2] row_mask:0xf bank_mask:0xf bound_ctrl:1
	v_pk_fma_f32 v[180:181], v[110:111], v[102:103], v[180:181] op_sel_hi:[0,1,1]
	v_pk_fma_f32 v[182:183], v[110:111], v[104:105], v[182:183] op_sel_hi:[0,1,1]
	v_add_f32_dpp v178, v178, v178 quad_perm:[2,3,0,1] row_mask:0xf bank_mask:0xf bound_ctrl:1
	v_pk_mul_f32 v[184:185], v[60:61], v[156:157]
	v_pk_fma_f32 v[184:185], v[58:59], v[158:159], v[184:185]
	v_add_f32_dpp v178, v178, v178 row_half_mirror row_mask:0xf bank_mask:0xf bound_ctrl:1
	v_add_f32_e32 v162, v184, v185
	ds_read_b32 v146, v79 offset:8960
	v_add_f32_dpp v178, v178, v178 row_mirror row_mask:0xf bank_mask:0xf bound_ctrl:1
	ds_read_b128 v[142:145], v78 offset:8192
	ds_read_b128 v[156:159], v78 offset:8704
	v_pk_fma_f32 v[60:61], v[178:179], v[98:99], v[180:181] op_sel_hi:[0,1,1] neg_lo:[1,0,0] neg_hi:[1,0,0]
	v_pk_fma_f32 v[58:59], v[178:179], v[100:101], v[182:183] op_sel_hi:[0,1,1] neg_lo:[1,0,0] neg_hi:[1,0,0]
	s_waitcnt lgkmcnt(7)
	v_pk_mul_f32 v[176:177], v[60:61], v[116:117]
	v_pk_fma_f32 v[176:177], v[58:59], v[118:119], v[176:177]
	ds_read_b128 v[94:97], v78 offset:9472
	ds_read_b128 v[90:93], v78 offset:9216
	v_pk_fma_f32 v[180:181], v[60:61], v[112:113], v[60:61] neg_lo:[1,0,0] neg_hi:[1,0,0]
	v_add_f32_e32 v178, v176, v177
	v_pk_fma_f32 v[182:183], v[58:59], v[114:115], v[58:59] neg_lo:[1,0,0] neg_hi:[1,0,0]
	ds_read_b128 v[102:105], v78 offset:9984
	v_add_f32_dpp v178, v178, v178 quad_perm:[1,0,3,2] row_mask:0xf bank_mask:0xf bound_ctrl:1
	v_pk_fma_f32 v[180:181], v[132:133], v[124:125], v[180:181] op_sel_hi:[0,1,1]
	v_pk_fma_f32 v[182:183], v[132:133], v[126:127], v[182:183] op_sel_hi:[0,1,1]
	v_add_f32_dpp v178, v178, v178 quad_perm:[2,3,0,1] row_mask:0xf bank_mask:0xf bound_ctrl:1
	v_pk_mul_f32 v[184:185], v[60:61], v[106:107]
	v_pk_fma_f32 v[184:185], v[58:59], v[108:109], v[184:185]
	v_add_f32_dpp v178, v178, v178 row_half_mirror row_mask:0xf bank_mask:0xf bound_ctrl:1
	v_add_f32_e32 v163, v184, v185
	ds_read_b32 v110, v79 offset:10496
	v_add_f32_dpp v178, v178, v178 row_mirror row_mask:0xf bank_mask:0xf bound_ctrl:1
	ds_read_b128 v[98:101], v78 offset:9728
	ds_read_b128 v[106:109], v78 offset:10240
	v_pk_fma_f32 v[60:61], v[178:179], v[120:121], v[180:181] op_sel_hi:[0,1,1] neg_lo:[1,0,0] neg_hi:[1,0,0]
	v_pk_fma_f32 v[58:59], v[178:179], v[122:123], v[182:183] op_sel_hi:[0,1,1] neg_lo:[1,0,0] neg_hi:[1,0,0]
	s_waitcnt lgkmcnt(7)
	v_pk_mul_f32 v[176:177], v[60:61], v[138:139]
	v_pk_fma_f32 v[176:177], v[58:59], v[140:141], v[176:177]
	ds_read_b128 v[116:119], v78 offset:11008
	ds_read_b128 v[112:115], v78 offset:10752
	v_pk_fma_f32 v[180:181], v[60:61], v[134:135], v[60:61] neg_lo:[1,0,0] neg_hi:[1,0,0]
	v_add_f32_e32 v178, v176, v177
	v_pk_fma_f32 v[182:183], v[58:59], v[136:137], v[58:59] neg_lo:[1,0,0] neg_hi:[1,0,0]
	ds_read_b128 v[124:127], v78 offset:11520
	v_add_f32_dpp v178, v178, v178 quad_perm:[1,0,3,2] row_mask:0xf bank_mask:0xf bound_ctrl:1
	v_pk_fma_f32 v[180:181], v[146:147], v[152:153], v[180:181] op_sel_hi:[0,1,1]
	v_pk_fma_f32 v[182:183], v[146:147], v[154:155], v[182:183] op_sel_hi:[0,1,1]
	v_add_f32_dpp v178, v178, v178 quad_perm:[2,3,0,1] row_mask:0xf bank_mask:0xf bound_ctrl:1
	v_pk_mul_f32 v[184:185], v[60:61], v[128:129]
	v_pk_fma_f32 v[184:185], v[58:59], v[130:131], v[184:185]
	v_add_f32_dpp v178, v178, v178 row_half_mirror row_mask:0xf bank_mask:0xf bound_ctrl:1
	v_add_f32_e32 v164, v184, v185
	ds_read_b32 v132, v79 offset:12032
	v_add_f32_dpp v178, v178, v178 row_mirror row_mask:0xf bank_mask:0xf bound_ctrl:1
	ds_read_b128 v[120:123], v78 offset:11264
	ds_read_b128 v[128:131], v78 offset:11776
	v_pk_fma_f32 v[60:61], v[178:179], v[142:143], v[180:181] op_sel_hi:[0,1,1] neg_lo:[1,0,0] neg_hi:[1,0,0]
	v_pk_fma_f32 v[58:59], v[178:179], v[144:145], v[182:183] op_sel_hi:[0,1,1] neg_lo:[1,0,0] neg_hi:[1,0,0]
	s_waitcnt lgkmcnt(7)
; __device__ __forceinline__ float lo2f(unsigned w) { return __uint_as_float(w << 16); }
; __device__ __forceinline__ float hi2f(unsigned w) { return __uint_as_float(w & 0xffff0000u); }
; __device__ __forceinline__ void rwkv_scan_unit(CP p, int u, char* smem) {
;     ...
;   auto lwrite = [&](int bi) {
; #pragma unroll
;     for (int x = 0; x < 3; ++x) {
;       const int e = tid + x * 256, tok = e / 48, rem = e % 48, vec = rem >> 3, part = rem & 7;
;       float* d = buf + bi * 6144 + tok * 384 + vec * 64 + part * 8;
;       *reinterpret_cast<float4*>(d) = make_float4(lo2f(st[x].x), hi2f(st[x].x), lo2f(st[x].y), hi2f(st[x].y));
;       *reinterpret_cast<float4*>(d + 4) = make_float4(lo2f(st[x].z), hi2f(st[x].z), lo2f(st[x].w), hi2f(st[x].w));
;     }
;   };
;     ...
;     for (int s = 0; s < 16; ++s) {
;       const float* sb = cb + (s + 1) * 384;
;       const float4 om_n = *reinterpret_cast<const float4*>(sb + j * 4);
;       const float4 kk_n = *reinterpret_cast<const float4*>(sb + 64 + j * 4);
;       const float4 bb_n = *reinterpret_cast<const float4*>(sb + 128 + j * 4);
;       const float4 kp_n = *reinterpret_cast<const float4*>(sb + 192 + j * 4);
;       const float4 rr_n = *reinterpret_cast<const float4*>(sb + 256 + j * 4);
;       const float vv_n = sb[320 + rowv];
;       __builtin_amdgcn_sched_barrier(0);
;       float d = s0 * kk.x + s1 * kk.y + s2 * kk.z + s3 * kk.w;
;       d = allreduce16(d);
;       const float sa = -d;
;       s0 = fmaf(-s0, om.x, s0); s1 = fmaf(-s1, om.y, s1); s2 = fmaf(-s2, om.z, s2); s3 = fmaf(-s3, om.w, s3);
;       s0 = fmaf(sa, bb.x, s0); s1 = fmaf(sa, bb.y, s1); s2 = fmaf(sa, bb.z, s2); s3 = fmaf(sa, bb.w, s3);
;       s0 = fmaf(vv, kp.x, s0); s1 = fmaf(vv, kp.y, s1); s2 = fmaf(vv, kp.z, s2); s3 = fmaf(vv, kp.w, s3);
;       float y = s0 * rr.x + s1 * rr.y + s2 * rr.z + s3 * rr.w;
;       y = allreduce16(y);
;       if (j == s) ykeep = y;
;       om = om_n; kk = kk_n; bb = bb_n; kp = kp_n; rr = rr_n; vv = vv_n;
;     }
	v_pk_mul_f32 v[176:177], v[60:61], v[94:95]
	v_pk_fma_f32 v[176:177], v[58:59], v[96:97], v[176:177]
	ds_read_b128 v[138:141], v78 offset:12544
	ds_read_b128 v[134:137], v78 offset:12288
	v_pk_fma_f32 v[180:181], v[60:61], v[90:91], v[60:61] neg_lo:[1,0,0] neg_hi:[1,0,0]
	v_add_f32_e32 v178, v176, v177
	v_pk_fma_f32 v[182:183], v[58:59], v[92:93], v[58:59] neg_lo:[1,0,0] neg_hi:[1,0,0]
	ds_read_b128 v[152:155], v78 offset:13056
	v_add_f32_dpp v178, v178, v178 quad_perm:[1,0,3,2] row_mask:0xf bank_mask:0xf bound_ctrl:1
	v_pk_fma_f32 v[180:181], v[110:111], v[102:103], v[180:181] op_sel_hi:[0,1,1]
	v_pk_fma_f32 v[182:183], v[110:111], v[104:105], v[182:183] op_sel_hi:[0,1,1]
	v_add_f32_dpp v178, v178, v178 quad_perm:[2,3,0,1] row_mask:0xf bank_mask:0xf bound_ctrl:1
	v_pk_mul_f32 v[184:185], v[60:61], v[156:157]
	v_pk_fma_f32 v[184:185], v[58:59], v[158:159], v[184:185]
	v_add_f32_dpp v178, v178, v178 row_half_mirror row_mask:0xf bank_mask:0xf bound_ctrl:1
	v_add_f32_e32 v165, v184, v185
	ds_read_b32 v146, v79 offset:13568
	v_add_f32_dpp v178, v178, v178 row_mirror row_mask:0xf bank_mask:0xf bound_ctrl:1
	ds_read_b128 v[142:145], v78 offset:12800
	ds_read_b128 v[156:159], v78 offset:13312
	v_pk_fma_f32 v[60:61], v[178:179], v[98:99], v[180:181] op_sel_hi:[0,1,1] neg_lo:[1,0,0] neg_hi:[1,0,0]
	v_pk_fma_f32 v[58:59], v[178:179], v[100:101], v[182:183] op_sel_hi:[0,1,1] neg_lo:[1,0,0] neg_hi:[1,0,0]
	s_waitcnt lgkmcnt(7)
	v_pk_mul_f32 v[176:177], v[60:61], v[116:117]
	v_pk_fma_f32 v[176:177], v[58:59], v[118:119], v[176:177]
	ds_read_b128 v[94:97], v78 offset:14080
	ds_read_b128 v[90:93], v78 offset:13824
	v_pk_fma_f32 v[180:181], v[60:61], v[112:113], v[60:61] neg_lo:[1,0,0] neg_hi:[1,0,0]
	v_add_f32_e32 v178, v176, v177
	v_pk_fma_f32 v[182:183], v[58:59], v[114:115], v[58:59] neg_lo:[1,0,0] neg_hi:[1,0,0]
	ds_read_b128 v[102:105], v78 offset:14592
	v_add_f32_dpp v178, v178, v178 quad_perm:[1,0,3,2] row_mask:0xf bank_mask:0xf bound_ctrl:1
	v_pk_fma_f32 v[180:181], v[132:133], v[124:125], v[180:181] op_sel_hi:[0,1,1]
	v_pk_fma_f32 v[182:183], v[132:133], v[126:127], v[182:183] op_sel_hi:[0,1,1]
	v_add_f32_dpp v178, v178, v178 quad_perm:[2,3,0,1] row_mask:0xf bank_mask:0xf bound_ctrl:1
	v_pk_mul_f32 v[184:185], v[60:61], v[106:107]
	v_pk_fma_f32 v[184:185], v[58:59], v[108:109], v[184:185]
	v_add_f32_dpp v178, v178, v178 row_half_mirror row_mask:0xf bank_mask:0xf bound_ctrl:1
	v_add_f32_e32 v166, v184, v185
	ds_read_b32 v110, v79 offset:15104
	v_add_f32_dpp v178, v178, v178 row_mirror row_mask:0xf bank_mask:0xf bound_ctrl:1
	ds_read_b128 v[98:101], v78 offset:14336
	ds_read_b128 v[106:109], v78 offset:14848
	v_pk_fma_f32 v[60:61], v[178:179], v[120:121], v[180:181] op_sel_hi:[0,1,1] neg_lo:[1,0,0] neg_hi:[1,0,0]
	v_pk_fma_f32 v[58:59], v[178:179], v[122:123], v[182:183] op_sel_hi:[0,1,1] neg_lo:[1,0,0] neg_hi:[1,0,0]
	s_waitcnt vmcnt(3)
	s_add_i32 s2, s63, 24576
	v_lshl_add_u32 v12, v67, 2, s2
	v_add3_u32 v18, v12, v68, v69
	v_lshlrev_b32_e32 v12, 16, v198
	v_and_b32_e32 v13, 0xffff0000, v198
	v_lshlrev_b32_e32 v14, 16, v199
	v_and_b32_e32 v15, 0xffff0000, v199
	ds_write_b128 v18, v[12:15]
	v_lshlrev_b32_e32 v12, 16, v200
	v_and_b32_e32 v13, 0xffff0000, v200
	v_lshlrev_b32_e32 v14, 16, v201
	v_and_b32_e32 v15, 0xffff0000, v201
	ds_write_b128 v18, v[12:15] offset:16
	v_lshl_add_u32 v12, v70, 2, s2
	v_add3_u32 v18, v12, v71, v72
	v_lshlrev_b32_e32 v12, 16, v202
	v_and_b32_e32 v13, 0xffff0000, v202
	v_lshlrev_b32_e32 v14, 16, v203
	v_and_b32_e32 v15, 0xffff0000, v203
	ds_write_b128 v18, v[12:15]
	v_lshlrev_b32_e32 v12, 16, v204
	v_and_b32_e32 v13, 0xffff0000, v204
	v_lshlrev_b32_e32 v14, 16, v205
	v_and_b32_e32 v15, 0xffff0000, v205
	ds_write_b128 v18, v[12:15] offset:16
	v_lshl_add_u32 v12, v73, 2, s2
	v_add3_u32 v18, v12, v74, v75
	v_lshlrev_b32_e32 v12, 16, v206
	v_and_b32_e32 v13, 0xffff0000, v206
	v_lshlrev_b32_e32 v14, 16, v207
	v_and_b32_e32 v15, 0xffff0000, v207
	ds_write_b128 v18, v[12:15]
	v_lshlrev_b32_e32 v12, 16, v208
	v_and_b32_e32 v13, 0xffff0000, v208
	v_lshlrev_b32_e32 v14, 16, v209
	v_and_b32_e32 v15, 0xffff0000, v209
	ds_write_b128 v18, v[12:15] offset:16
	s_waitcnt lgkmcnt(13)
	v_pk_mul_f32 v[176:177], v[60:61], v[138:139]
	v_pk_fma_f32 v[176:177], v[58:59], v[140:141], v[176:177]
	ds_read_b128 v[116:119], v78 offset:15616
	ds_read_b128 v[112:115], v78 offset:15360
	v_pk_fma_f32 v[180:181], v[60:61], v[134:135], v[60:61] neg_lo:[1,0,0] neg_hi:[1,0,0]
	v_add_f32_e32 v178, v176, v177
	v_pk_fma_f32 v[182:183], v[58:59], v[136:137], v[58:59] neg_lo:[1,0,0] neg_hi:[1,0,0]
	ds_read_b128 v[124:127], v78 offset:16128
	v_add_f32_dpp v178, v178, v178 quad_perm:[1,0,3,2] row_mask:0xf bank_mask:0xf bound_ctrl:1
	v_pk_fma_f32 v[180:181], v[146:147], v[152:153], v[180:181] op_sel_hi:[0,1,1]
	v_pk_fma_f32 v[182:183], v[146:147], v[154:155], v[182:183] op_sel_hi:[0,1,1]
	v_add_f32_dpp v178, v178, v178 quad_perm:[2,3,0,1] row_mask:0xf bank_mask:0xf bound_ctrl:1
	v_pk_mul_f32 v[184:185], v[60:61], v[128:129]
	v_pk_fma_f32 v[184:185], v[58:59], v[130:131], v[184:185]
	v_add_f32_dpp v178, v178, v178 row_half_mirror row_mask:0xf bank_mask:0xf bound_ctrl:1
	v_add_f32_e32 v167, v184, v185
	ds_read_b32 v132, v79 offset:16640
	v_add_f32_dpp v178, v178, v178 row_mirror row_mask:0xf bank_mask:0xf bound_ctrl:1
	ds_read_b128 v[120:123], v78 offset:15872
	ds_read_b128 v[128:131], v78 offset:16384
	v_pk_fma_f32 v[60:61], v[178:179], v[142:143], v[180:181] op_sel_hi:[0,1,1] neg_lo:[1,0,0] neg_hi:[1,0,0]
	v_pk_fma_f32 v[58:59], v[178:179], v[144:145], v[182:183] op_sel_hi:[0,1,1] neg_lo:[1,0,0] neg_hi:[1,0,0]
	s_waitcnt lgkmcnt(13)
; __device__ __forceinline__ void rwkv_scan_unit(CP p, int u, char* smem) {
;     ...
;     for (int s = 0; s < 16; ++s) {
;       const float* sb = cb + (s + 1) * 384;
;       const float4 om_n = *reinterpret_cast<const float4*>(sb + j * 4);
;       const float4 kk_n = *reinterpret_cast<const float4*>(sb + 64 + j * 4);
;       const float4 bb_n = *reinterpret_cast<const float4*>(sb + 128 + j * 4);
;       const float4 kp_n = *reinterpret_cast<const float4*>(sb + 192 + j * 4);
;       const float4 rr_n = *reinterpret_cast<const float4*>(sb + 256 + j * 4);
;       const float vv_n = sb[320 + rowv];
;       __builtin_amdgcn_sched_barrier(0);
;       float d = s0 * kk.x + s1 * kk.y + s2 * kk.z + s3 * kk.w;
;       d = allreduce16(d);
;       const float sa = -d;
;       s0 = fmaf(-s0, om.x, s0); s1 = fmaf(-s1, om.y, s1); s2 = fmaf(-s2, om.z, s2); s3 = fmaf(-s3, om.w, s3);
;       s0 = fmaf(sa, bb.x, s0); s1 = fmaf(sa, bb.y, s1); s2 = fmaf(sa, bb.z, s2); s3 = fmaf(sa, bb.w, s3);
;       s0 = fmaf(vv, kp.x, s0); s1 = fmaf(vv, kp.y, s1); s2 = fmaf(vv, kp.z, s2); s3 = fmaf(vv, kp.w, s3);
;       float y = s0 * rr.x + s1 * rr.y + s2 * rr.z + s3 * rr.w;
;       y = allreduce16(y);
;       if (j == s) ykeep = y;
;       om = om_n; kk = kk_n; bb = bb_n; kp = kp_n; rr = rr_n; vv = vv_n;
;     }
	v_pk_mul_f32 v[176:177], v[60:61], v[94:95]
	v_pk_fma_f32 v[176:177], v[58:59], v[96:97], v[176:177]
	ds_read_b128 v[138:141], v78 offset:17152
	ds_read_b128 v[134:137], v78 offset:16896
	v_pk_fma_f32 v[180:181], v[60:61], v[90:91], v[60:61] neg_lo:[1,0,0] neg_hi:[1,0,0]
	v_add_f32_e32 v178, v176, v177
	v_pk_fma_f32 v[182:183], v[58:59], v[92:93], v[58:59] neg_lo:[1,0,0] neg_hi:[1,0,0]
	ds_read_b128 v[152:155], v78 offset:17664
	v_add_f32_dpp v178, v178, v178 quad_perm:[1,0,3,2] row_mask:0xf bank_mask:0xf bound_ctrl:1
	v_pk_fma_f32 v[180:181], v[110:111], v[102:103], v[180:181] op_sel_hi:[0,1,1]
	v_pk_fma_f32 v[182:183], v[110:111], v[104:105], v[182:183] op_sel_hi:[0,1,1]
	v_add_f32_dpp v178, v178, v178 quad_perm:[2,3,0,1] row_mask:0xf bank_mask:0xf bound_ctrl:1
	v_pk_mul_f32 v[184:185], v[60:61], v[156:157]
	v_pk_fma_f32 v[184:185], v[58:59], v[158:159], v[184:185]
	v_add_f32_dpp v178, v178, v178 row_half_mirror row_mask:0xf bank_mask:0xf bound_ctrl:1
	v_add_f32_e32 v168, v184, v185
	ds_read_b32 v146, v79 offset:18176
	v_add_f32_dpp v178, v178, v178 row_mirror row_mask:0xf bank_mask:0xf bound_ctrl:1
	ds_read_b128 v[142:145], v78 offset:17408
	ds_read_b128 v[156:159], v78 offset:17920
	v_pk_fma_f32 v[60:61], v[178:179], v[98:99], v[180:181] op_sel_hi:[0,1,1] neg_lo:[1,0,0] neg_hi:[1,0,0]
	v_pk_fma_f32 v[58:59], v[178:179], v[100:101], v[182:183] op_sel_hi:[0,1,1] neg_lo:[1,0,0] neg_hi:[1,0,0]
	s_waitcnt lgkmcnt(7)
	v_pk_mul_f32 v[176:177], v[60:61], v[116:117]
	v_pk_fma_f32 v[176:177], v[58:59], v[118:119], v[176:177]
	ds_read_b128 v[94:97], v78 offset:18688
	ds_read_b128 v[90:93], v78 offset:18432
	v_pk_fma_f32 v[180:181], v[60:61], v[112:113], v[60:61] neg_lo:[1,0,0] neg_hi:[1,0,0]
	v_add_f32_e32 v178, v176, v177
	v_pk_fma_f32 v[182:183], v[58:59], v[114:115], v[58:59] neg_lo:[1,0,0] neg_hi:[1,0,0]
	ds_read_b128 v[102:105], v78 offset:19200
	v_add_f32_dpp v178, v178, v178 quad_perm:[1,0,3,2] row_mask:0xf bank_mask:0xf bound_ctrl:1
	v_pk_fma_f32 v[180:181], v[132:133], v[124:125], v[180:181] op_sel_hi:[0,1,1]
	v_pk_fma_f32 v[182:183], v[132:133], v[126:127], v[182:183] op_sel_hi:[0,1,1]
	v_add_f32_dpp v178, v178, v178 quad_perm:[2,3,0,1] row_mask:0xf bank_mask:0xf bound_ctrl:1
	v_pk_mul_f32 v[184:185], v[60:61], v[106:107]
	v_pk_fma_f32 v[184:185], v[58:59], v[108:109], v[184:185]
	v_add_f32_dpp v178, v178, v178 row_half_mirror row_mask:0xf bank_mask:0xf bound_ctrl:1
	v_add_f32_e32 v169, v184, v185
	ds_read_b32 v110, v79 offset:19712
	v_add_f32_dpp v178, v178, v178 row_mirror row_mask:0xf bank_mask:0xf bound_ctrl:1
	ds_read_b128 v[98:101], v78 offset:18944
	ds_read_b128 v[106:109], v78 offset:19456
	v_pk_fma_f32 v[60:61], v[178:179], v[120:121], v[180:181] op_sel_hi:[0,1,1] neg_lo:[1,0,0] neg_hi:[1,0,0]
	v_pk_fma_f32 v[58:59], v[178:179], v[122:123], v[182:183] op_sel_hi:[0,1,1] neg_lo:[1,0,0] neg_hi:[1,0,0]
	s_waitcnt lgkmcnt(7)
	v_pk_mul_f32 v[176:177], v[60:61], v[138:139]
	v_pk_fma_f32 v[176:177], v[58:59], v[140:141], v[176:177]
	ds_read_b128 v[116:119], v78 offset:20224
	ds_read_b128 v[112:115], v78 offset:19968
	v_pk_fma_f32 v[180:181], v[60:61], v[134:135], v[60:61] neg_lo:[1,0,0] neg_hi:[1,0,0]
	v_add_f32_e32 v178, v176, v177
	v_pk_fma_f32 v[182:183], v[58:59], v[136:137], v[58:59] neg_lo:[1,0,0] neg_hi:[1,0,0]
	ds_read_b128 v[124:127], v78 offset:20736
	v_add_f32_dpp v178, v178, v178 quad_perm:[1,0,3,2] row_mask:0xf bank_mask:0xf bound_ctrl:1
	v_pk_fma_f32 v[180:181], v[146:147], v[152:153], v[180:181] op_sel_hi:[0,1,1]
	v_pk_fma_f32 v[182:183], v[146:147], v[154:155], v[182:183] op_sel_hi:[0,1,1]
	v_add_f32_dpp v178, v178, v178 quad_perm:[2,3,0,1] row_mask:0xf bank_mask:0xf bound_ctrl:1
	v_pk_mul_f32 v[184:185], v[60:61], v[128:129]
	v_pk_fma_f32 v[184:185], v[58:59], v[130:131], v[184:185]
	v_add_f32_dpp v178, v178, v178 row_half_mirror row_mask:0xf bank_mask:0xf bound_ctrl:1
	v_add_f32_e32 v170, v184, v185
	ds_read_b32 v132, v79 offset:21248
	v_add_f32_dpp v178, v178, v178 row_mirror row_mask:0xf bank_mask:0xf bound_ctrl:1
	ds_read_b128 v[120:123], v78 offset:20480
	ds_read_b128 v[128:131], v78 offset:20992
	v_pk_fma_f32 v[60:61], v[178:179], v[142:143], v[180:181] op_sel_hi:[0,1,1] neg_lo:[1,0,0] neg_hi:[1,0,0]
	v_pk_fma_f32 v[58:59], v[178:179], v[144:145], v[182:183] op_sel_hi:[0,1,1] neg_lo:[1,0,0] neg_hi:[1,0,0]
	s_waitcnt lgkmcnt(7)
	v_pk_mul_f32 v[176:177], v[60:61], v[94:95]
	v_pk_fma_f32 v[176:177], v[58:59], v[96:97], v[176:177]
	ds_read_b128 v[138:141], v78 offset:21760
	ds_read_b128 v[134:137], v78 offset:21504
	v_pk_fma_f32 v[180:181], v[60:61], v[90:91], v[60:61] neg_lo:[1,0,0] neg_hi:[1,0,0]
	v_add_f32_e32 v178, v176, v177
	v_pk_fma_f32 v[182:183], v[58:59], v[92:93], v[58:59] neg_lo:[1,0,0] neg_hi:[1,0,0]
	ds_read_b128 v[152:155], v78 offset:22272
	v_add_f32_dpp v178, v178, v178 quad_perm:[1,0,3,2] row_mask:0xf bank_mask:0xf bound_ctrl:1
	v_pk_fma_f32 v[180:181], v[110:111], v[102:103], v[180:181] op_sel_hi:[0,1,1]
	v_pk_fma_f32 v[182:183], v[110:111], v[104:105], v[182:183] op_sel_hi:[0,1,1]
	v_add_f32_dpp v178, v178, v178 quad_perm:[2,3,0,1] row_mask:0xf bank_mask:0xf bound_ctrl:1
	v_pk_mul_f32 v[184:185], v[60:61], v[156:157]
	v_pk_fma_f32 v[184:185], v[58:59], v[158:159], v[184:185]
	v_add_f32_dpp v178, v178, v178 row_half_mirror row_mask:0xf bank_mask:0xf bound_ctrl:1
	v_add_f32_e32 v171, v184, v185
	ds_read_b32 v146, v79 offset:22784
	v_add_f32_dpp v178, v178, v178 row_mirror row_mask:0xf bank_mask:0xf bound_ctrl:1
	ds_read_b128 v[142:145], v78 offset:22016
	ds_read_b128 v[156:159], v78 offset:22528
	v_pk_fma_f32 v[60:61], v[178:179], v[98:99], v[180:181] op_sel_hi:[0,1,1] neg_lo:[1,0,0] neg_hi:[1,0,0]
	v_pk_fma_f32 v[58:59], v[178:179], v[100:101], v[182:183] op_sel_hi:[0,1,1] neg_lo:[1,0,0] neg_hi:[1,0,0]
	s_waitcnt lgkmcnt(7)
; __device__ __forceinline__ void rwkv_scan_unit(CP p, int u, char* smem) {
;     ...
;     for (int s = 0; s < 16; ++s) {
;       const float* sb = cb + (s + 1) * 384;
;       const float4 om_n = *reinterpret_cast<const float4*>(sb + j * 4);
;       const float4 kk_n = *reinterpret_cast<const float4*>(sb + 64 + j * 4);
;       const float4 bb_n = *reinterpret_cast<const float4*>(sb + 128 + j * 4);
;       const float4 kp_n = *reinterpret_cast<const float4*>(sb + 192 + j * 4);
;       const float4 rr_n = *reinterpret_cast<const float4*>(sb + 256 + j * 4);
;       const float vv_n = sb[320 + rowv];
;       __builtin_amdgcn_sched_barrier(0);
;       float d = s0 * kk.x + s1 * kk.y + s2 * kk.z + s3 * kk.w;
;       d = allreduce16(d);
;       const float sa = -d;
;       s0 = fmaf(-s0, om.x, s0); s1 = fmaf(-s1, om.y, s1); s2 = fmaf(-s2, om.z, s2); s3 = fmaf(-s3, om.w, s3);
;       s0 = fmaf(sa, bb.x, s0); s1 = fmaf(sa, bb.y, s1); s2 = fmaf(sa, bb.z, s2); s3 = fmaf(sa, bb.w, s3);
;       s0 = fmaf(vv, kp.x, s0); s1 = fmaf(vv, kp.y, s1); s2 = fmaf(vv, kp.z, s2); s3 = fmaf(vv, kp.w, s3);
;       float y = s0 * rr.x + s1 * rr.y + s2 * rr.z + s3 * rr.w;
;       y = allreduce16(y);
;       if (j == s) ykeep = y;
;       om = om_n; kk = kk_n; bb = bb_n; kp = kp_n; rr = rr_n; vv = vv_n;
;     }
	v_pk_mul_f32 v[176:177], v[60:61], v[116:117]
	v_pk_fma_f32 v[176:177], v[58:59], v[118:119], v[176:177]
	ds_read_b128 v[94:97], v78 offset:23296
	ds_read_b128 v[90:93], v78 offset:23040
	v_pk_fma_f32 v[180:181], v[60:61], v[112:113], v[60:61] neg_lo:[1,0,0] neg_hi:[1,0,0]
	v_add_f32_e32 v178, v176, v177
	v_pk_fma_f32 v[182:183], v[58:59], v[114:115], v[58:59] neg_lo:[1,0,0] neg_hi:[1,0,0]
	ds_read_b128 v[102:105], v78 offset:23808
	v_add_f32_dpp v178, v178, v178 quad_perm:[1,0,3,2] row_mask:0xf bank_mask:0xf bound_ctrl:1
	v_pk_fma_f32 v[180:181], v[132:133], v[124:125], v[180:181] op_sel_hi:[0,1,1]
	v_pk_fma_f32 v[182:183], v[132:133], v[126:127], v[182:183] op_sel_hi:[0,1,1]
	v_add_f32_dpp v178, v178, v178 quad_perm:[2,3,0,1] row_mask:0xf bank_mask:0xf bound_ctrl:1
	v_pk_mul_f32 v[184:185], v[60:61], v[106:107]
	v_pk_fma_f32 v[184:185], v[58:59], v[108:109], v[184:185]
	v_add_f32_dpp v178, v178, v178 row_half_mirror row_mask:0xf bank_mask:0xf bound_ctrl:1
	v_add_f32_e32 v172, v184, v185
	ds_read_b32 v110, v79 offset:24320
	v_add_f32_dpp v178, v178, v178 row_mirror row_mask:0xf bank_mask:0xf bound_ctrl:1
	ds_read_b128 v[98:101], v78 offset:23552
	ds_read_b128 v[106:109], v78 offset:24064
	v_pk_fma_f32 v[60:61], v[178:179], v[120:121], v[180:181] op_sel_hi:[0,1,1] neg_lo:[1,0,0] neg_hi:[1,0,0]
	v_pk_fma_f32 v[58:59], v[178:179], v[122:123], v[182:183] op_sel_hi:[0,1,1] neg_lo:[1,0,0] neg_hi:[1,0,0]
	s_waitcnt lgkmcnt(7)
	v_pk_mul_f32 v[176:177], v[60:61], v[138:139]
	v_pk_fma_f32 v[176:177], v[58:59], v[140:141], v[176:177]
	v_pk_fma_f32 v[180:181], v[60:61], v[134:135], v[60:61] neg_lo:[1,0,0] neg_hi:[1,0,0]
	v_add_f32_e32 v178, v176, v177
	v_pk_fma_f32 v[182:183], v[58:59], v[136:137], v[58:59] neg_lo:[1,0,0] neg_hi:[1,0,0]
	s_nop 0
	v_add_f32_dpp v178, v178, v178 quad_perm:[1,0,3,2] row_mask:0xf bank_mask:0xf bound_ctrl:1
	v_pk_fma_f32 v[180:181], v[146:147], v[152:153], v[180:181] op_sel_hi:[0,1,1]
	v_pk_fma_f32 v[182:183], v[146:147], v[154:155], v[182:183] op_sel_hi:[0,1,1]
	v_add_f32_dpp v178, v178, v178 quad_perm:[2,3,0,1] row_mask:0xf bank_mask:0xf bound_ctrl:1
	v_pk_mul_f32 v[184:185], v[60:61], v[128:129]
	v_pk_fma_f32 v[184:185], v[58:59], v[130:131], v[184:185]
	v_add_f32_dpp v178, v178, v178 row_half_mirror row_mask:0xf bank_mask:0xf bound_ctrl:1
	v_add_f32_e32 v173, v184, v185
	s_nop 0
	v_add_f32_dpp v178, v178, v178 row_mirror row_mask:0xf bank_mask:0xf bound_ctrl:1
	v_pk_fma_f32 v[60:61], v[178:179], v[142:143], v[180:181] op_sel_hi:[0,1,1] neg_lo:[1,0,0] neg_hi:[1,0,0]
	v_pk_fma_f32 v[58:59], v[178:179], v[144:145], v[182:183] op_sel_hi:[0,1,1] neg_lo:[1,0,0] neg_hi:[1,0,0]
	s_waitcnt lgkmcnt(1)
	v_pk_mul_f32 v[176:177], v[60:61], v[94:95]
	v_pk_fma_f32 v[176:177], v[58:59], v[96:97], v[176:177]
	v_pk_fma_f32 v[180:181], v[60:61], v[90:91], v[60:61] neg_lo:[1,0,0] neg_hi:[1,0,0]
	v_add_f32_e32 v178, v176, v177
	v_pk_fma_f32 v[182:183], v[58:59], v[92:93], v[58:59] neg_lo:[1,0,0] neg_hi:[1,0,0]
	s_nop 0
	v_add_f32_dpp v178, v178, v178 quad_perm:[1,0,3,2] row_mask:0xf bank_mask:0xf bound_ctrl:1
	v_pk_fma_f32 v[180:181], v[110:111], v[102:103], v[180:181] op_sel_hi:[0,1,1]
	v_pk_fma_f32 v[182:183], v[110:111], v[104:105], v[182:183] op_sel_hi:[0,1,1]
	v_add_f32_dpp v178, v178, v178 quad_perm:[2,3,0,1] row_mask:0xf bank_mask:0xf bound_ctrl:1
	v_pk_mul_f32 v[184:185], v[60:61], v[156:157]
	v_pk_fma_f32 v[184:185], v[58:59], v[158:159], v[184:185]
	v_add_f32_dpp v178, v178, v178 row_half_mirror row_mask:0xf bank_mask:0xf bound_ctrl:1
	v_add_f32_e32 v174, v184, v185
	s_nop 0
	v_add_f32_dpp v178, v178, v178 row_mirror row_mask:0xf bank_mask:0xf bound_ctrl:1
	v_pk_fma_f32 v[60:61], v[178:179], v[98:99], v[180:181] op_sel_hi:[0,1,1] neg_lo:[1,0,0] neg_hi:[1,0,0]
	v_pk_fma_f32 v[58:59], v[178:179], v[100:101], v[182:183] op_sel_hi:[0,1,1] neg_lo:[1,0,0] neg_hi:[1,0,0]
	s_waitcnt lgkmcnt(0)
; __device__ __forceinline__ bf16_t f2bf(float f) { return (bf16_t)(pack2(f, 0.f) & 0xffffu); }
; __device__ __forceinline__ int tidx() { int t = threadIdx.x & 255; asm volatile("" : "+v"(t)); return t; }
; __device__ __forceinline__ int half_id() { int t = (int)(threadIdx.x >> 8); asm volatile("" : "+v"(t)); return __builtin_amdgcn_readfirstlane(t); }
; #define LAS3 __attribute__((address_space(3)))
; __device__ __forceinline__ void half_barrier(char* smem_half) {
;   const int h = half_id();
;   LAS3 unsigned* cnt = (LAS3 unsigned*)(smem_half + (2 - h) * 65536 + 8 + h * 4);
;   asm volatile("s_waitcnt lgkmcnt(0)" ::: "memory");
;   if ((tidx() & 63) == 0) {
;     const unsigned old = __hip_atomic_fetch_add(cnt, 1u, __ATOMIC_RELAXED, __HIP_MEMORY_SCOPE_WORKGROUP);
;     const unsigned target = (old & ~3u) + 4u;
;     while (__hip_atomic_load(cnt, __ATOMIC_RELAXED, __HIP_MEMORY_SCOPE_WORKGROUP) < target) __builtin_amdgcn_s_sleep(1);
;   }
; __device__ __forceinline__ void rwkv_scan_unit(CP p, int u, char* smem) {
;     ...
;       float y = s0 * rr.x + s1 * rr.y + s2 * rr.z + s3 * rr.w;
;       y = allreduce16(y);
;       if (j == s) ykeep = y;
;       om = om_n; kk = kk_n; bb = bb_n; kp = kp_n; rr = rr_n; vv = vv_n;
;     }
;     Y[(size_t)(rowof(b, c * 16) + j) * 1024 + 256 + h * 64 + rowv] = f2bf(ykeep);
;     if (c + 1 < NCH) lwrite((c + 1) & 1);
;     half_barrier(smem);
	v_pk_mul_f32 v[184:185], v[60:61], v[106:107]
	v_pk_fma_f32 v[184:185], v[58:59], v[108:109], v[184:185]
	v_add_f32_e32 v175, v184, v185
	v_add_f32_dpp v160, v160, v160 row_ror:8 row_mask:0xf bank_mask:0x3 bound_ctrl:1
	v_add_f32_dpp v161, v161, v161 row_ror:8 row_mask:0xf bank_mask:0x3 bound_ctrl:1
	v_add_f32_dpp v162, v162, v162 row_ror:8 row_mask:0xf bank_mask:0x3 bound_ctrl:1
	v_add_f32_dpp v163, v163, v163 row_ror:8 row_mask:0xf bank_mask:0x3 bound_ctrl:1
	v_add_f32_dpp v164, v164, v164 row_ror:8 row_mask:0xf bank_mask:0x3 bound_ctrl:1
	v_add_f32_dpp v165, v165, v165 row_ror:8 row_mask:0xf bank_mask:0x3 bound_ctrl:1
	v_add_f32_dpp v166, v166, v166 row_ror:8 row_mask:0xf bank_mask:0x3 bound_ctrl:1
	v_add_f32_dpp v167, v167, v167 row_ror:8 row_mask:0xf bank_mask:0x3 bound_ctrl:1
	v_add_f32_dpp v160, v168, v168 row_ror:8 row_mask:0xf bank_mask:0xc bound_ctrl:1
	v_add_f32_dpp v161, v169, v169 row_ror:8 row_mask:0xf bank_mask:0xc bound_ctrl:1
	v_add_f32_dpp v162, v170, v170 row_ror:8 row_mask:0xf bank_mask:0xc bound_ctrl:1
	v_add_f32_dpp v163, v171, v171 row_ror:8 row_mask:0xf bank_mask:0xc bound_ctrl:1
	v_add_f32_dpp v164, v172, v172 row_ror:8 row_mask:0xf bank_mask:0xc bound_ctrl:1
	v_add_f32_dpp v165, v173, v173 row_ror:8 row_mask:0xf bank_mask:0xc bound_ctrl:1
	v_add_f32_dpp v166, v174, v174 row_ror:8 row_mask:0xf bank_mask:0xc bound_ctrl:1
	v_add_f32_dpp v167, v175, v175 row_ror:8 row_mask:0xf bank_mask:0xc bound_ctrl:1
	v_add_f32_dpp v160, v160, v160 row_half_mirror row_mask:0xf bank_mask:0x5 bound_ctrl:1
	v_add_f32_dpp v161, v161, v161 row_half_mirror row_mask:0xf bank_mask:0x5 bound_ctrl:1
	v_add_f32_dpp v162, v162, v162 row_half_mirror row_mask:0xf bank_mask:0x5 bound_ctrl:1
	v_add_f32_dpp v163, v163, v163 row_half_mirror row_mask:0xf bank_mask:0x5 bound_ctrl:1
	v_add_f32_dpp v160, v164, v164 row_half_mirror row_mask:0xf bank_mask:0xa bound_ctrl:1
	v_add_f32_dpp v161, v165, v165 row_half_mirror row_mask:0xf bank_mask:0xa bound_ctrl:1
	v_add_f32_dpp v162, v166, v166 row_half_mirror row_mask:0xf bank_mask:0xa bound_ctrl:1
	v_add_f32_dpp v163, v167, v167 row_half_mirror row_mask:0xf bank_mask:0xa bound_ctrl:1
	v_and_b32_e32 v186, 2, v76
	v_cmp_ne_u32_e32 vcc, 0, v186
	v_and_b32_e32 v186, 1, v76
	s_nop 0
	v_cndmask_b32_e32 v187, v160, v162, vcc
	v_cndmask_b32_e32 v188, v162, v160, vcc
	v_cndmask_b32_e32 v189, v161, v163, vcc
	v_cndmask_b32_e32 v190, v163, v161, vcc
	v_cmp_ne_u32_e32 vcc, 0, v186
	v_add_f32_dpp v160, v188, v187 quad_perm:[2,3,0,1] row_mask:0xf bank_mask:0xf bound_ctrl:1
	v_add_f32_dpp v161, v190, v189 quad_perm:[2,3,0,1] row_mask:0xf bank_mask:0xf bound_ctrl:1
	v_cndmask_b32_e32 v187, v160, v161, vcc
	v_cndmask_b32_e32 v188, v161, v160, vcc
	s_nop 1
	v_add_f32_dpp v82, v188, v187 quad_perm:[1,0,3,2] row_mask:0xf bank_mask:0xf bound_ctrl:1
	s_lshl_b32 s5, s4, 4
	s_add_i32 s5, s5, s11
	s_cmp_eq_u32 s4, 0
	s_cselect_b32 s5, s10, s5
	v_or_b32_e32 v12, s5, v76
	v_ashrrev_i32_e32 v13, 31, v12
	v_lshlrev_b64 v[12:13], 11, v[12:13]
	v_cvt_pk_bf16_f32 v14, v82, s0
	v_lshl_add_u64 v[12:13], v[56:57], 0, v[12:13]
	global_store_short v[12:13], v14, off
	s_waitcnt lgkmcnt(0)
	s_mov_b64 s[12:13], exec
	s_mov_b64 exec, 1
	ds_add_u32 v193, v195 offset:8
	s_mov_b64 exec, s[12:13]
	v_add_u32_e32 v194, 4, v194

; __device__ __forceinline__ void rwkv_scan_unit(CP p, int u, char* smem) {
;     ...
;   for (int c = 0; c < NCH; ++c) {
;     if (c + 1 < NCH) gload(c + 1);
;     const float* cb = buf + (c & 1) * 6144;
;     float ykeep = 0.f;
;     float4 om = *reinterpret_cast<const float4*>(cb + j * 4);
;     float4 kk = *reinterpret_cast<const float4*>(cb + 64 + j * 4);
;     float4 bb = *reinterpret_cast<const float4*>(cb + 128 + j * 4);
;     float4 kp = *reinterpret_cast<const float4*>(cb + 192 + j * 4);
;     float4 rr = *reinterpret_cast<const float4*>(cb + 256 + j * 4);
;     float vv = cb[320 + rowv];
; #pragma unroll 2
;     for (int s = 0; s < 16; ++s) {
;       const float* sb = cb + (s + 1) * 384;
;       const float4 om_n = *reinterpret_cast<const float4*>(sb + j * 4);
;       const float4 kk_n = *reinterpret_cast<const float4*>(sb + 64 + j * 4);
;       const float4 bb_n = *reinterpret_cast<const float4*>(sb + 128 + j * 4);
;       const float4 kp_n = *reinterpret_cast<const float4*>(sb + 192 + j * 4);
;       const float4 rr_n = *reinterpret_cast<const float4*>(sb + 256 + j * 4);
;       const float vv_n = sb[320 + rowv];
.Lrw_bdoneE:
	s_mov_b32 s4, s28
	s_cmpk_lt_i32 s28, 0x81
	s_cbranch_scc0 .Lrw_exit
.Lrw_headO:
	s_add_i32 s28, s4, 1
	s_add_i32 s13, s63, 24576
	v_lshl_add_u32 v78, v77, 2, s13
	v_lshl_add_u32 v79, v48, 2, s13
	s_cmpk_gt_i32 s4, 0x7e
	s_cbranch_scc0 .Lrw_doglO
	s_waitcnt vmcnt(0)
	s_branch .Lrw_skipglO
.Lrw_doglO:
	s_add_i32 s5, s4, 2
	s_lshl_b32 s5, s5, 4
	s_add_i32 s5, s5, s11
	v_add_u32_e32 v198, s5, v63
	v_add_u32_e32 v202, s5, v65
	v_add_u32_e32 v206, s5, v66
	v_mad_i64_i32 v[198:199], s[12:13], v198, s66, v[50:51]
	v_mad_i64_i32 v[202:203], s[12:13], v202, s66, v[52:53]
	v_mad_i64_i32 v[206:207], s[12:13], v206, s66, v[54:55]
	global_load_dwordx4 v[198:201], v[198:199], off
	global_load_dwordx4 v[202:205], v[202:203], off
	global_load_dwordx4 v[206:209], v[206:207], off
.Lrw_skipglO:
	ds_read_b128 v[94:97], v78 offset:256
	ds_read_b128 v[90:93], v78 offset:0
	ds_read_b128 v[102:105], v78 offset:768
	ds_read_b32 v110, v79 offset:1280
	ds_read_b128 v[98:101], v78 offset:512
	ds_read_b128 v[106:109], v78 offset:1024
	ds_read_b128 v[116:119], v78 offset:1792
	ds_read_b128 v[112:115], v78 offset:1536
	ds_read_b128 v[124:127], v78 offset:2304
	ds_read_b32 v132, v79 offset:2816
	ds_read_b128 v[120:123], v78 offset:2048
	ds_read_b128 v[128:131], v78 offset:2560
	s_waitcnt lgkmcnt(7)
	v_pk_mul_f32 v[176:177], v[60:61], v[94:95]
	v_pk_fma_f32 v[176:177], v[58:59], v[96:97], v[176:177]
	ds_read_b128 v[138:141], v78 offset:3328
	ds_read_b128 v[134:137], v78 offset:3072
	v_pk_fma_f32 v[180:181], v[60:61], v[90:91], v[60:61] neg_lo:[1,0,0] neg_hi:[1,0,0]
	v_add_f32_e32 v178, v176, v177
	v_pk_fma_f32 v[182:183], v[58:59], v[92:93], v[58:59] neg_lo:[1,0,0] neg_hi:[1,0,0]
	ds_read_b128 v[152:155], v78 offset:3840
	v_add_f32_dpp v178, v178, v178 quad_perm:[1,0,3,2] row_mask:0xf bank_mask:0xf bound_ctrl:1
	v_pk_fma_f32 v[180:181], v[110:111], v[102:103], v[180:181] op_sel_hi:[0,1,1]
	v_pk_fma_f32 v[182:183], v[110:111], v[104:105], v[182:183] op_sel_hi:[0,1,1]
	v_add_f32_dpp v178, v178, v178 quad_perm:[2,3,0,1] row_mask:0xf bank_mask:0xf bound_ctrl:1
	ds_read_b32 v146, v79 offset:4352
	ds_read_b128 v[142:145], v78 offset:3584
	v_add_f32_dpp v178, v178, v178 row_half_mirror row_mask:0xf bank_mask:0xf bound_ctrl:1
	ds_read_b128 v[156:159], v78 offset:4096
	s_nop 0
	v_add_f32_dpp v178, v178, v178 row_mirror row_mask:0xf bank_mask:0xf bound_ctrl:1
	v_pk_fma_f32 v[60:61], v[178:179], v[98:99], v[180:181] op_sel_hi:[0,1,1] neg_lo:[1,0,0] neg_hi:[1,0,0]
	v_pk_fma_f32 v[58:59], v[178:179], v[100:101], v[182:183] op_sel_hi:[0,1,1] neg_lo:[1,0,0] neg_hi:[1,0,0]
	s_waitcnt lgkmcnt(7)
	v_pk_mul_f32 v[176:177], v[60:61], v[116:117]
	v_pk_fma_f32 v[176:177], v[58:59], v[118:119], v[176:177]
	ds_read_b128 v[94:97], v78 offset:4864
	ds_read_b128 v[90:93], v78 offset:4608
	v_pk_fma_f32 v[180:181], v[60:61], v[112:113], v[60:61] neg_lo:[1,0,0] neg_hi:[1,0,0]
	v_add_f32_e32 v178, v176, v177
	v_pk_fma_f32 v[182:183], v[58:59], v[114:115], v[58:59] neg_lo:[1,0,0] neg_hi:[1,0,0]
	ds_read_b128 v[102:105], v78 offset:5376
	v_add_f32_dpp v178, v178, v178 quad_perm:[1,0,3,2] row_mask:0xf bank_mask:0xf bound_ctrl:1
	v_pk_fma_f32 v[180:181], v[132:133], v[124:125], v[180:181] op_sel_hi:[0,1,1]
	v_pk_fma_f32 v[182:183], v[132:133], v[126:127], v[182:183] op_sel_hi:[0,1,1]
	v_add_f32_dpp v178, v178, v178 quad_perm:[2,3,0,1] row_mask:0xf bank_mask:0xf bound_ctrl:1
	v_pk_mul_f32 v[184:185], v[60:61], v[106:107]
	v_pk_fma_f32 v[184:185], v[58:59], v[108:109], v[184:185]
	v_add_f32_dpp v178, v178, v178 row_half_mirror row_mask:0xf bank_mask:0xf bound_ctrl:1
	v_add_f32_e32 v160, v184, v185
	ds_read_b32 v110, v79 offset:5888
	v_add_f32_dpp v178, v178, v178 row_mirror row_mask:0xf bank_mask:0xf bound_ctrl:1
	ds_read_b128 v[98:101], v78 offset:5120
	ds_read_b128 v[106:109], v78 offset:5632
	v_pk_fma_f32 v[60:61], v[178:179], v[120:121], v[180:181] op_sel_hi:[0,1,1] neg_lo:[1,0,0] neg_hi:[1,0,0]
	v_pk_fma_f32 v[58:59], v[178:179], v[122:123], v[182:183] op_sel_hi:[0,1,1] neg_lo:[1,0,0] neg_hi:[1,0,0]
	s_waitcnt lgkmcnt(7)
	v_pk_mul_f32 v[176:177], v[60:61], v[138:139]
	v_pk_fma_f32 v[176:177], v[58:59], v[140:141], v[176:177]
	ds_read_b128 v[116:119], v78 offset:6400
	ds_read_b128 v[112:115], v78 offset:6144
	v_pk_fma_f32 v[180:181], v[60:61], v[134:135], v[60:61] neg_lo:[1,0,0] neg_hi:[1,0,0]
	v_add_f32_e32 v178, v176, v177
	v_pk_fma_f32 v[182:183], v[58:59], v[136:137], v[58:59] neg_lo:[1,0,0] neg_hi:[1,0,0]
	ds_read_b128 v[124:127], v78 offset:6912
	v_add_f32_dpp v178, v178, v178 quad_perm:[1,0,3,2] row_mask:0xf bank_mask:0xf bound_ctrl:1
	v_pk_fma_f32 v[180:181], v[146:147], v[152:153], v[180:181] op_sel_hi:[0,1,1]
	v_pk_fma_f32 v[182:183], v[146:147], v[154:155], v[182:183] op_sel_hi:[0,1,1]
	v_add_f32_dpp v178, v178, v178 quad_perm:[2,3,0,1] row_mask:0xf bank_mask:0xf bound_ctrl:1
	v_pk_mul_f32 v[184:185], v[60:61], v[128:129]
	v_pk_fma_f32 v[184:185], v[58:59], v[130:131], v[184:185]
	v_add_f32_dpp v178, v178, v178 row_half_mirror row_mask:0xf bank_mask:0xf bound_ctrl:1
	v_add_f32_e32 v161, v184, v185
	ds_read_b32 v132, v79 offset:7424
	v_add_f32_dpp v178, v178, v178 row_mirror row_mask:0xf bank_mask:0xf bound_ctrl:1
	ds_read_b128 v[120:123], v78 offset:6656
	ds_read_b128 v[128:131], v78 offset:7168
	v_pk_fma_f32 v[60:61], v[178:179], v[142:143], v[180:181] op_sel_hi:[0,1,1] neg_lo:[1,0,0] neg_hi:[1,0,0]
	v_pk_fma_f32 v[58:59], v[178:179], v[144:145], v[182:183] op_sel_hi:[0,1,1] neg_lo:[1,0,0] neg_hi:[1,0,0]
	s_waitcnt lgkmcnt(7)
; __device__ __forceinline__ void rwkv_scan_unit(CP p, int u, char* smem) {
;     ...
;     for (int s = 0; s < 16; ++s) {
;       const float* sb = cb + (s + 1) * 384;
;       const float4 om_n = *reinterpret_cast<const float4*>(sb + j * 4);
;       const float4 kk_n = *reinterpret_cast<const float4*>(sb + 64 + j * 4);
;       const float4 bb_n = *reinterpret_cast<const float4*>(sb + 128 + j * 4);
;       const float4 kp_n = *reinterpret_cast<const float4*>(sb + 192 + j * 4);
;       const float4 rr_n = *reinterpret_cast<const float4*>(sb + 256 + j * 4);
;       const float vv_n = sb[320 + rowv];
;       __builtin_amdgcn_sched_barrier(0);
;       float d = s0 * kk.x + s1 * kk.y + s2 * kk.z + s3 * kk.w;
;       d = allreduce16(d);
;       const float sa = -d;
;       s0 = fmaf(-s0, om.x, s0); s1 = fmaf(-s1, om.y, s1); s2 = fmaf(-s2, om.z, s2); s3 = fmaf(-s3, om.w, s3);
;       s0 = fmaf(sa, bb.x, s0); s1 = fmaf(sa, bb.y, s1); s2 = fmaf(sa, bb.z, s2); s3 = fmaf(sa, bb.w, s3);
;       s0 = fmaf(vv, kp.x, s0); s1 = fmaf(vv, kp.y, s1); s2 = fmaf(vv, kp.z, s2); s3 = fmaf(vv, kp.w, s3);
;       float y = s0 * rr.x + s1 * rr.y + s2 * rr.z + s3 * rr.w;
;       y = allreduce16(y);
;       if (j == s) ykeep = y;
;       om = om_n; kk = kk_n; bb = bb_n; kp = kp_n; rr = rr_n; vv = vv_n;
;     }
	v_pk_mul_f32 v[176:177], v[60:61], v[94:95]
	v_pk_fma_f32 v[176:177], v[58:59], v[96:97], v[176:177]
	ds_read_b128 v[138:141], v78 offset:7936
	ds_read_b128 v[134:137], v78 offset:7680
	v_pk_fma_f32 v[180:181], v[60:61], v[90:91], v[60:61] neg_lo:[1,0,0] neg_hi:[1,0,0]
	v_add_f32_e32 v178, v176, v177
	v_pk_fma_f32 v[182:183], v[58:59], v[92:93], v[58:59] neg_lo:[1,0,0] neg_hi:[1,0,0]
	ds_read_b128 v[152:155], v78 offset:8448
	v_add_f32_dpp v178, v178, v178 quad_perm:[1,0,3,2] row_mask:0xf bank_mask:0xf bound_ctrl:1
	v_pk_fma_f32 v[180:181], v[110:111], v[102:103], v[180:181] op_sel_hi:[0,1,1]
	v_pk_fma_f32 v[182:183], v[110:111], v[104:105], v[182:183] op_sel_hi:[0,1,1]
	v_add_f32_dpp v178, v178, v178 quad_perm:[2,3,0,1] row_mask:0xf bank_mask:0xf bound_ctrl:1
	v_pk_mul_f32 v[184:185], v[60:61], v[156:157]
	v_pk_fma_f32 v[184:185], v[58:59], v[158:159], v[184:185]
	v_add_f32_dpp v178, v178, v178 row_half_mirror row_mask:0xf bank_mask:0xf bound_ctrl:1
	v_add_f32_e32 v162, v184, v185
	ds_read_b32 v146, v79 offset:8960
	v_add_f32_dpp v178, v178, v178 row_mirror row_mask:0xf bank_mask:0xf bound_ctrl:1
	ds_read_b128 v[142:145], v78 offset:8192
	ds_read_b128 v[156:159], v78 offset:8704
	v_pk_fma_f32 v[60:61], v[178:179], v[98:99], v[180:181] op_sel_hi:[0,1,1] neg_lo:[1,0,0] neg_hi:[1,0,0]
	v_pk_fma_f32 v[58:59], v[178:179], v[100:101], v[182:183] op_sel_hi:[0,1,1] neg_lo:[1,0,0] neg_hi:[1,0,0]
	s_waitcnt lgkmcnt(7)
	v_pk_mul_f32 v[176:177], v[60:61], v[116:117]
	v_pk_fma_f32 v[176:177], v[58:59], v[118:119], v[176:177]
	ds_read_b128 v[94:97], v78 offset:9472
	ds_read_b128 v[90:93], v78 offset:9216
	v_pk_fma_f32 v[180:181], v[60:61], v[112:113], v[60:61] neg_lo:[1,0,0] neg_hi:[1,0,0]
	v_add_f32_e32 v178, v176, v177
	v_pk_fma_f32 v[182:183], v[58:59], v[114:115], v[58:59] neg_lo:[1,0,0] neg_hi:[1,0,0]
	ds_read_b128 v[102:105], v78 offset:9984
	v_add_f32_dpp v178, v178, v178 quad_perm:[1,0,3,2] row_mask:0xf bank_mask:0xf bound_ctrl:1
	v_pk_fma_f32 v[180:181], v[132:133], v[124:125], v[180:181] op_sel_hi:[0,1,1]
	v_pk_fma_f32 v[182:183], v[132:133], v[126:127], v[182:183] op_sel_hi:[0,1,1]
	v_add_f32_dpp v178, v178, v178 quad_perm:[2,3,0,1] row_mask:0xf bank_mask:0xf bound_ctrl:1
	v_pk_mul_f32 v[184:185], v[60:61], v[106:107]
	v_pk_fma_f32 v[184:185], v[58:59], v[108:109], v[184:185]
	v_add_f32_dpp v178, v178, v178 row_half_mirror row_mask:0xf bank_mask:0xf bound_ctrl:1
	v_add_f32_e32 v163, v184, v185
	ds_read_b32 v110, v79 offset:10496
	v_add_f32_dpp v178, v178, v178 row_mirror row_mask:0xf bank_mask:0xf bound_ctrl:1
	ds_read_b128 v[98:101], v78 offset:9728
	ds_read_b128 v[106:109], v78 offset:10240
	v_pk_fma_f32 v[60:61], v[178:179], v[120:121], v[180:181] op_sel_hi:[0,1,1] neg_lo:[1,0,0] neg_hi:[1,0,0]
	v_pk_fma_f32 v[58:59], v[178:179], v[122:123], v[182:183] op_sel_hi:[0,1,1] neg_lo:[1,0,0] neg_hi:[1,0,0]
	s_waitcnt lgkmcnt(7)
	v_pk_mul_f32 v[176:177], v[60:61], v[138:139]
	v_pk_fma_f32 v[176:177], v[58:59], v[140:141], v[176:177]
	ds_read_b128 v[116:119], v78 offset:11008
	ds_read_b128 v[112:115], v78 offset:10752
	v_pk_fma_f32 v[180:181], v[60:61], v[134:135], v[60:61] neg_lo:[1,0,0] neg_hi:[1,0,0]
	v_add_f32_e32 v178, v176, v177
	v_pk_fma_f32 v[182:183], v[58:59], v[136:137], v[58:59] neg_lo:[1,0,0] neg_hi:[1,0,0]
	ds_read_b128 v[124:127], v78 offset:11520
	v_add_f32_dpp v178, v178, v178 quad_perm:[1,0,3,2] row_mask:0xf bank_mask:0xf bound_ctrl:1
	v_pk_fma_f32 v[180:181], v[146:147], v[152:153], v[180:181] op_sel_hi:[0,1,1]
	v_pk_fma_f32 v[182:183], v[146:147], v[154:155], v[182:183] op_sel_hi:[0,1,1]
	v_add_f32_dpp v178, v178, v178 quad_perm:[2,3,0,1] row_mask:0xf bank_mask:0xf bound_ctrl:1
	v_pk_mul_f32 v[184:185], v[60:61], v[128:129]
	v_pk_fma_f32 v[184:185], v[58:59], v[130:131], v[184:185]
	v_add_f32_dpp v178, v178, v178 row_half_mirror row_mask:0xf bank_mask:0xf bound_ctrl:1
	v_add_f32_e32 v164, v184, v185
	ds_read_b32 v132, v79 offset:12032
	v_add_f32_dpp v178, v178, v178 row_mirror row_mask:0xf bank_mask:0xf bound_ctrl:1
	ds_read_b128 v[120:123], v78 offset:11264
	ds_read_b128 v[128:131], v78 offset:11776
	v_pk_fma_f32 v[60:61], v[178:179], v[142:143], v[180:181] op_sel_hi:[0,1,1] neg_lo:[1,0,0] neg_hi:[1,0,0]
	v_pk_fma_f32 v[58:59], v[178:179], v[144:145], v[182:183] op_sel_hi:[0,1,1] neg_lo:[1,0,0] neg_hi:[1,0,0]
	s_waitcnt lgkmcnt(7)
	v_pk_mul_f32 v[176:177], v[60:61], v[94:95]
	v_pk_fma_f32 v[176:177], v[58:59], v[96:97], v[176:177]
	ds_read_b128 v[138:141], v78 offset:12544
	ds_read_b128 v[134:137], v78 offset:12288
	v_pk_fma_f32 v[180:181], v[60:61], v[90:91], v[60:61] neg_lo:[1,0,0] neg_hi:[1,0,0]
	v_add_f32_e32 v178, v176, v177
	v_pk_fma_f32 v[182:183], v[58:59], v[92:93], v[58:59] neg_lo:[1,0,0] neg_hi:[1,0,0]
	ds_read_b128 v[152:155], v78 offset:13056
	v_add_f32_dpp v178, v178, v178 quad_perm:[1,0,3,2] row_mask:0xf bank_mask:0xf bound_ctrl:1
	v_pk_fma_f32 v[180:181], v[110:111], v[102:103], v[180:181] op_sel_hi:[0,1,1]
	v_pk_fma_f32 v[182:183], v[110:111], v[104:105], v[182:183] op_sel_hi:[0,1,1]
	v_add_f32_dpp v178, v178, v178 quad_perm:[2,3,0,1] row_mask:0xf bank_mask:0xf bound_ctrl:1
	v_pk_mul_f32 v[184:185], v[60:61], v[156:157]
	v_pk_fma_f32 v[184:185], v[58:59], v[158:159], v[184:185]
	v_add_f32_dpp v178, v178, v178 row_half_mirror row_mask:0xf bank_mask:0xf bound_ctrl:1
	v_add_f32_e32 v165, v184, v185
	ds_read_b32 v146, v79 offset:13568
	v_add_f32_dpp v178, v178, v178 row_mirror row_mask:0xf bank_mask:0xf bound_ctrl:1
	ds_read_b128 v[142:145], v78 offset:12800
	ds_read_b128 v[156:159], v78 offset:13312
	v_pk_fma_f32 v[60:61], v[178:179], v[98:99], v[180:181] op_sel_hi:[0,1,1] neg_lo:[1,0,0] neg_hi:[1,0,0]
	v_pk_fma_f32 v[58:59], v[178:179], v[100:101], v[182:183] op_sel_hi:[0,1,1] neg_lo:[1,0,0] neg_hi:[1,0,0]
	s_waitcnt lgkmcnt(7)
; __device__ __forceinline__ void rwkv_scan_unit(CP p, int u, char* smem) {
;     ...
;   auto lwrite = [&](int bi) {
; #pragma unroll
;     for (int x = 0; x < 3; ++x) {
;       const int e = tid + x * 256, tok = e / 48, rem = e % 48, vec = rem >> 3, part = rem & 7;
;       float* d = buf + bi * 6144 + tok * 384 + vec * 64 + part * 8;
;       *reinterpret_cast<float4*>(d) = make_float4(lo2f(st[x].x), hi2f(st[x].x), lo2f(st[x].y), hi2f(st[x].y));
;       *reinterpret_cast<float4*>(d + 4) = make_float4(lo2f(st[x].z), hi2f(st[x].z), lo2f(st[x].w), hi2f(st[x].w));
;     }
;   };
;   half_barrier(smem);
;   gload(0);
;   lwrite(0);
;   half_barrier(smem);
;   constexpr int NCH = T / 16;
;   for (int c = 0; c < NCH; ++c) {
;     if (c + 1 < NCH) gload(c + 1);
;     const float* cb = buf + (c & 1) * 6144;
;     float ykeep = 0.f;
;     float4 om = *reinterpret_cast<const float4*>(cb + j * 4);
;     float4 kk = *reinterpret_cast<const float4*>(cb + 64 + j * 4);
;     float4 bb = *reinterpret_cast<const float4*>(cb + 128 + j * 4);
;     float4 kp = *reinterpret_cast<const float4*>(cb + 192 + j * 4);
;     float4 rr = *reinterpret_cast<const float4*>(cb + 256 + j * 4);
;     float vv = cb[320 + rowv];
; #pragma unroll 2
;     for (int s = 0; s < 16; ++s) {
;       const float* sb = cb + (s + 1) * 384;
;       const float4 om_n = *reinterpret_cast<const float4*>(sb + j * 4);
;       const float4 kk_n = *reinterpret_cast<const float4*>(sb + 64 + j * 4);
;       const float4 bb_n = *reinterpret_cast<const float4*>(sb + 128 + j * 4);
;       const float4 kp_n = *reinterpret_cast<const float4*>(sb + 192 + j * 4);
;       const float4 rr_n = *reinterpret_cast<const float4*>(sb + 256 + j * 4);
;       const float vv_n = sb[320 + rowv];
;       __builtin_amdgcn_sched_barrier(0);
;       float d = s0 * kk.x + s1 * kk.y + s2 * kk.z + s3 * kk.w;
;       d = allreduce16(d);
;       const float sa = -d;
;       s0 = fmaf(-s0, om.x, s0); s1 = fmaf(-s1, om.y, s1); s2 = fmaf(-s2, om.z, s2); s3 = fmaf(-s3, om.w, s3);
;       s0 = fmaf(sa, bb.x, s0); s1 = fmaf(sa, bb.y, s1); s2 = fmaf(sa, bb.z, s2); s3 = fmaf(sa, bb.w, s3);
;       s0 = fmaf(vv, kp.x, s0); s1 = fmaf(vv, kp.y, s1); s2 = fmaf(vv, kp.z, s2); s3 = fmaf(vv, kp.w, s3);
;       float y = s0 * rr.x + s1 * rr.y + s2 * rr.z + s3 * rr.w;
;       y = allreduce16(y);
;       if (j == s) ykeep = y;
	v_pk_mul_f32 v[176:177], v[60:61], v[116:117]
	v_pk_fma_f32 v[176:177], v[58:59], v[118:119], v[176:177]
	ds_read_b128 v[94:97], v78 offset:14080
	ds_read_b128 v[90:93], v78 offset:13824
	v_pk_fma_f32 v[180:181], v[60:61], v[112:113], v[60:61] neg_lo:[1,0,0] neg_hi:[1,0,0]
	v_add_f32_e32 v178, v176, v177
	v_pk_fma_f32 v[182:183], v[58:59], v[114:115], v[58:59] neg_lo:[1,0,0] neg_hi:[1,0,0]
	ds_read_b128 v[102:105], v78 offset:14592
	v_add_f32_dpp v178, v178, v178 quad_perm:[1,0,3,2] row_mask:0xf bank_mask:0xf bound_ctrl:1
	v_pk_fma_f32 v[180:181], v[132:133], v[124:125], v[180:181] op_sel_hi:[0,1,1]
	v_pk_fma_f32 v[182:183], v[132:133], v[126:127], v[182:183] op_sel_hi:[0,1,1]
	v_add_f32_dpp v178, v178, v178 quad_perm:[2,3,0,1] row_mask:0xf bank_mask:0xf bound_ctrl:1
	v_pk_mul_f32 v[184:185], v[60:61], v[106:107]
	v_pk_fma_f32 v[184:185], v[58:59], v[108:109], v[184:185]
	v_add_f32_dpp v178, v178, v178 row_half_mirror row_mask:0xf bank_mask:0xf bound_ctrl:1
	v_add_f32_e32 v166, v184, v185
	ds_read_b32 v110, v79 offset:15104
	v_add_f32_dpp v178, v178, v178 row_mirror row_mask:0xf bank_mask:0xf bound_ctrl:1
	ds_read_b128 v[98:101], v78 offset:14336
	ds_read_b128 v[106:109], v78 offset:14848
	v_pk_fma_f32 v[60:61], v[178:179], v[120:121], v[180:181] op_sel_hi:[0,1,1] neg_lo:[1,0,0] neg_hi:[1,0,0]
	v_pk_fma_f32 v[58:59], v[178:179], v[122:123], v[182:183] op_sel_hi:[0,1,1] neg_lo:[1,0,0] neg_hi:[1,0,0]
	s_waitcnt vmcnt(3)
	s_mov_b32 s2, s63
	v_lshl_add_u32 v12, v67, 2, s2
	v_add3_u32 v18, v12, v68, v69
	v_lshlrev_b32_e32 v12, 16, v0
	v_and_b32_e32 v13, 0xffff0000, v0
	v_lshlrev_b32_e32 v14, 16, v1
	v_and_b32_e32 v15, 0xffff0000, v1
	ds_write_b128 v18, v[12:15]
	v_lshlrev_b32_e32 v12, 16, v2
	v_and_b32_e32 v13, 0xffff0000, v2
	v_lshlrev_b32_e32 v14, 16, v3
	v_and_b32_e32 v15, 0xffff0000, v3
	ds_write_b128 v18, v[12:15] offset:16
	v_lshl_add_u32 v12, v70, 2, s2
	v_add3_u32 v18, v12, v71, v72
	v_lshlrev_b32_e32 v12, 16, v4
	v_and_b32_e32 v13, 0xffff0000, v4
	v_lshlrev_b32_e32 v14, 16, v5
	v_and_b32_e32 v15, 0xffff0000, v5
	ds_write_b128 v18, v[12:15]
	v_lshlrev_b32_e32 v12, 16, v6
	v_and_b32_e32 v13, 0xffff0000, v6
	v_lshlrev_b32_e32 v14, 16, v7
	v_and_b32_e32 v15, 0xffff0000, v7
	ds_write_b128 v18, v[12:15] offset:16
	v_lshl_add_u32 v12, v73, 2, s2
	v_add3_u32 v18, v12, v74, v75
	v_lshlrev_b32_e32 v12, 16, v8
	v_and_b32_e32 v13, 0xffff0000, v8
	v_lshlrev_b32_e32 v14, 16, v9
	v_and_b32_e32 v15, 0xffff0000, v9
	ds_write_b128 v18, v[12:15]
	v_lshlrev_b32_e32 v12, 16, v10
	v_and_b32_e32 v13, 0xffff0000, v10
	v_lshlrev_b32_e32 v14, 16, v11
	v_and_b32_e32 v15, 0xffff0000, v11
	ds_write_b128 v18, v[12:15] offset:16
	s_waitcnt lgkmcnt(13)
	v_pk_mul_f32 v[176:177], v[60:61], v[138:139]
	v_pk_fma_f32 v[176:177], v[58:59], v[140:141], v[176:177]
	ds_read_b128 v[116:119], v78 offset:15616
	ds_read_b128 v[112:115], v78 offset:15360
	v_pk_fma_f32 v[180:181], v[60:61], v[134:135], v[60:61] neg_lo:[1,0,0] neg_hi:[1,0,0]
	v_add_f32_e32 v178, v176, v177
	v_pk_fma_f32 v[182:183], v[58:59], v[136:137], v[58:59] neg_lo:[1,0,0] neg_hi:[1,0,0]
	ds_read_b128 v[124:127], v78 offset:16128
	v_add_f32_dpp v178, v178, v178 quad_perm:[1,0,3,2] row_mask:0xf bank_mask:0xf bound_ctrl:1
	v_pk_fma_f32 v[180:181], v[146:147], v[152:153], v[180:181] op_sel_hi:[0,1,1]
	v_pk_fma_f32 v[182:183], v[146:147], v[154:155], v[182:183] op_sel_hi:[0,1,1]
	v_add_f32_dpp v178, v178, v178 quad_perm:[2,3,0,1] row_mask:0xf bank_mask:0xf bound_ctrl:1
	v_pk_mul_f32 v[184:185], v[60:61], v[128:129]
	v_pk_fma_f32 v[184:185], v[58:59], v[130:131], v[184:185]
	v_add_f32_dpp v178, v178, v178 row_half_mirror row_mask:0xf bank_mask:0xf bound_ctrl:1
	v_add_f32_e32 v167, v184, v185
	ds_read_b32 v132, v79 offset:16640
	v_add_f32_dpp v178, v178, v178 row_mirror row_mask:0xf bank_mask:0xf bound_ctrl:1
	ds_read_b128 v[120:123], v78 offset:15872
	ds_read_b128 v[128:131], v78 offset:16384
	v_pk_fma_f32 v[60:61], v[178:179], v[142:143], v[180:181] op_sel_hi:[0,1,1] neg_lo:[1,0,0] neg_hi:[1,0,0]
	v_pk_fma_f32 v[58:59], v[178:179], v[144:145], v[182:183] op_sel_hi:[0,1,1] neg_lo:[1,0,0] neg_hi:[1,0,0]
	s_waitcnt lgkmcnt(13)
	v_pk_mul_f32 v[176:177], v[60:61], v[94:95]
	v_pk_fma_f32 v[176:177], v[58:59], v[96:97], v[176:177]
	ds_read_b128 v[138:141], v78 offset:17152
	ds_read_b128 v[134:137], v78 offset:16896
	v_pk_fma_f32 v[180:181], v[60:61], v[90:91], v[60:61] neg_lo:[1,0,0] neg_hi:[1,0,0]
	v_add_f32_e32 v178, v176, v177
	v_pk_fma_f32 v[182:183], v[58:59], v[92:93], v[58:59] neg_lo:[1,0,0] neg_hi:[1,0,0]
	ds_read_b128 v[152:155], v78 offset:17664
	v_add_f32_dpp v178, v178, v178 quad_perm:[1,0,3,2] row_mask:0xf bank_mask:0xf bound_ctrl:1
	v_pk_fma_f32 v[180:181], v[110:111], v[102:103], v[180:181] op_sel_hi:[0,1,1]
	v_pk_fma_f32 v[182:183], v[110:111], v[104:105], v[182:183] op_sel_hi:[0,1,1]
	v_add_f32_dpp v178, v178, v178 quad_perm:[2,3,0,1] row_mask:0xf bank_mask:0xf bound_ctrl:1
	v_pk_mul_f32 v[184:185], v[60:61], v[156:157]
	v_pk_fma_f32 v[184:185], v[58:59], v[158:159], v[184:185]
	v_add_f32_dpp v178, v178, v178 row_half_mirror row_mask:0xf bank_mask:0xf bound_ctrl:1
	v_add_f32_e32 v168, v184, v185
	ds_read_b32 v146, v79 offset:18176
	v_add_f32_dpp v178, v178, v178 row_mirror row_mask:0xf bank_mask:0xf bound_ctrl:1
	ds_read_b128 v[142:145], v78 offset:17408
	ds_read_b128 v[156:159], v78 offset:17920
	v_pk_fma_f32 v[60:61], v[178:179], v[98:99], v[180:181] op_sel_hi:[0,1,1] neg_lo:[1,0,0] neg_hi:[1,0,0]
	v_pk_fma_f32 v[58:59], v[178:179], v[100:101], v[182:183] op_sel_hi:[0,1,1] neg_lo:[1,0,0] neg_hi:[1,0,0]
	s_waitcnt lgkmcnt(7)
; __device__ __forceinline__ void rwkv_scan_unit(CP p, int u, char* smem) {
;     ...
;     for (int s = 0; s < 16; ++s) {
;       const float* sb = cb + (s + 1) * 384;
;       const float4 om_n = *reinterpret_cast<const float4*>(sb + j * 4);
;       const float4 kk_n = *reinterpret_cast<const float4*>(sb + 64 + j * 4);
;       const float4 bb_n = *reinterpret_cast<const float4*>(sb + 128 + j * 4);
;       const float4 kp_n = *reinterpret_cast<const float4*>(sb + 192 + j * 4);
;       const float4 rr_n = *reinterpret_cast<const float4*>(sb + 256 + j * 4);
;       const float vv_n = sb[320 + rowv];
;       __builtin_amdgcn_sched_barrier(0);
;       float d = s0 * kk.x + s1 * kk.y + s2 * kk.z + s3 * kk.w;
;       d = allreduce16(d);
;       const float sa = -d;
;       s0 = fmaf(-s0, om.x, s0); s1 = fmaf(-s1, om.y, s1); s2 = fmaf(-s2, om.z, s2); s3 = fmaf(-s3, om.w, s3);
;       s0 = fmaf(sa, bb.x, s0); s1 = fmaf(sa, bb.y, s1); s2 = fmaf(sa, bb.z, s2); s3 = fmaf(sa, bb.w, s3);
;       s0 = fmaf(vv, kp.x, s0); s1 = fmaf(vv, kp.y, s1); s2 = fmaf(vv, kp.z, s2); s3 = fmaf(vv, kp.w, s3);
;       float y = s0 * rr.x + s1 * rr.y + s2 * rr.z + s3 * rr.w;
;       y = allreduce16(y);
;       if (j == s) ykeep = y;
;       om = om_n; kk = kk_n; bb = bb_n; kp = kp_n; rr = rr_n; vv = vv_n;
;     }
	v_pk_mul_f32 v[176:177], v[60:61], v[116:117]
	v_pk_fma_f32 v[176:177], v[58:59], v[118:119], v[176:177]
	ds_read_b128 v[94:97], v78 offset:18688
	ds_read_b128 v[90:93], v78 offset:18432
	v_pk_fma_f32 v[180:181], v[60:61], v[112:113], v[60:61] neg_lo:[1,0,0] neg_hi:[1,0,0]
	v_add_f32_e32 v178, v176, v177
	v_pk_fma_f32 v[182:183], v[58:59], v[114:115], v[58:59] neg_lo:[1,0,0] neg_hi:[1,0,0]
	ds_read_b128 v[102:105], v78 offset:19200
	v_add_f32_dpp v178, v178, v178 quad_perm:[1,0,3,2] row_mask:0xf bank_mask:0xf bound_ctrl:1
	v_pk_fma_f32 v[180:181], v[132:133], v[124:125], v[180:181] op_sel_hi:[0,1,1]
	v_pk_fma_f32 v[182:183], v[132:133], v[126:127], v[182:183] op_sel_hi:[0,1,1]
	v_add_f32_dpp v178, v178, v178 quad_perm:[2,3,0,1] row_mask:0xf bank_mask:0xf bound_ctrl:1
	v_pk_mul_f32 v[184:185], v[60:61], v[106:107]
	v_pk_fma_f32 v[184:185], v[58:59], v[108:109], v[184:185]
	v_add_f32_dpp v178, v178, v178 row_half_mirror row_mask:0xf bank_mask:0xf bound_ctrl:1
	v_add_f32_e32 v169, v184, v185
	ds_read_b32 v110, v79 offset:19712
	v_add_f32_dpp v178, v178, v178 row_mirror row_mask:0xf bank_mask:0xf bound_ctrl:1
	ds_read_b128 v[98:101], v78 offset:18944
	ds_read_b128 v[106:109], v78 offset:19456
	v_pk_fma_f32 v[60:61], v[178:179], v[120:121], v[180:181] op_sel_hi:[0,1,1] neg_lo:[1,0,0] neg_hi:[1,0,0]
	v_pk_fma_f32 v[58:59], v[178:179], v[122:123], v[182:183] op_sel_hi:[0,1,1] neg_lo:[1,0,0] neg_hi:[1,0,0]
	s_waitcnt lgkmcnt(7)
	v_pk_mul_f32 v[176:177], v[60:61], v[138:139]
	v_pk_fma_f32 v[176:177], v[58:59], v[140:141], v[176:177]
	ds_read_b128 v[116:119], v78 offset:20224
	ds_read_b128 v[112:115], v78 offset:19968
	v_pk_fma_f32 v[180:181], v[60:61], v[134:135], v[60:61] neg_lo:[1,0,0] neg_hi:[1,0,0]
	v_add_f32_e32 v178, v176, v177
	v_pk_fma_f32 v[182:183], v[58:59], v[136:137], v[58:59] neg_lo:[1,0,0] neg_hi:[1,0,0]
	ds_read_b128 v[124:127], v78 offset:20736
	v_add_f32_dpp v178, v178, v178 quad_perm:[1,0,3,2] row_mask:0xf bank_mask:0xf bound_ctrl:1
	v_pk_fma_f32 v[180:181], v[146:147], v[152:153], v[180:181] op_sel_hi:[0,1,1]
	v_pk_fma_f32 v[182:183], v[146:147], v[154:155], v[182:183] op_sel_hi:[0,1,1]
	v_add_f32_dpp v178, v178, v178 quad_perm:[2,3,0,1] row_mask:0xf bank_mask:0xf bound_ctrl:1
	v_pk_mul_f32 v[184:185], v[60:61], v[128:129]
	v_pk_fma_f32 v[184:185], v[58:59], v[130:131], v[184:185]
	v_add_f32_dpp v178, v178, v178 row_half_mirror row_mask:0xf bank_mask:0xf bound_ctrl:1
	v_add_f32_e32 v170, v184, v185
	ds_read_b32 v132, v79 offset:21248
	v_add_f32_dpp v178, v178, v178 row_mirror row_mask:0xf bank_mask:0xf bound_ctrl:1
	ds_read_b128 v[120:123], v78 offset:20480
	ds_read_b128 v[128:131], v78 offset:20992
	v_pk_fma_f32 v[60:61], v[178:179], v[142:143], v[180:181] op_sel_hi:[0,1,1] neg_lo:[1,0,0] neg_hi:[1,0,0]
	v_pk_fma_f32 v[58:59], v[178:179], v[144:145], v[182:183] op_sel_hi:[0,1,1] neg_lo:[1,0,0] neg_hi:[1,0,0]
	s_waitcnt lgkmcnt(7)
	v_pk_mul_f32 v[176:177], v[60:61], v[94:95]
	v_pk_fma_f32 v[176:177], v[58:59], v[96:97], v[176:177]
	ds_read_b128 v[138:141], v78 offset:21760
	ds_read_b128 v[134:137], v78 offset:21504
	v_pk_fma_f32 v[180:181], v[60:61], v[90:91], v[60:61] neg_lo:[1,0,0] neg_hi:[1,0,0]
	v_add_f32_e32 v178, v176, v177
	v_pk_fma_f32 v[182:183], v[58:59], v[92:93], v[58:59] neg_lo:[1,0,0] neg_hi:[1,0,0]
	ds_read_b128 v[152:155], v78 offset:22272
	v_add_f32_dpp v178, v178, v178 quad_perm:[1,0,3,2] row_mask:0xf bank_mask:0xf bound_ctrl:1
	v_pk_fma_f32 v[180:181], v[110:111], v[102:103], v[180:181] op_sel_hi:[0,1,1]
	v_pk_fma_f32 v[182:183], v[110:111], v[104:105], v[182:183] op_sel_hi:[0,1,1]
	v_add_f32_dpp v178, v178, v178 quad_perm:[2,3,0,1] row_mask:0xf bank_mask:0xf bound_ctrl:1
	v_pk_mul_f32 v[184:185], v[60:61], v[156:157]
	v_pk_fma_f32 v[184:185], v[58:59], v[158:159], v[184:185]
	v_add_f32_dpp v178, v178, v178 row_half_mirror row_mask:0xf bank_mask:0xf bound_ctrl:1
	v_add_f32_e32 v171, v184, v185
	ds_read_b32 v146, v79 offset:22784
	v_add_f32_dpp v178, v178, v178 row_mirror row_mask:0xf bank_mask:0xf bound_ctrl:1
	ds_read_b128 v[142:145], v78 offset:22016
	ds_read_b128 v[156:159], v78 offset:22528
	v_pk_fma_f32 v[60:61], v[178:179], v[98:99], v[180:181] op_sel_hi:[0,1,1] neg_lo:[1,0,0] neg_hi:[1,0,0]
	v_pk_fma_f32 v[58:59], v[178:179], v[100:101], v[182:183] op_sel_hi:[0,1,1] neg_lo:[1,0,0] neg_hi:[1,0,0]
	s_waitcnt lgkmcnt(7)
	v_pk_mul_f32 v[176:177], v[60:61], v[116:117]
	v_pk_fma_f32 v[176:177], v[58:59], v[118:119], v[176:177]
	ds_read_b128 v[94:97], v78 offset:23296
	ds_read_b128 v[90:93], v78 offset:23040
	v_pk_fma_f32 v[180:181], v[60:61], v[112:113], v[60:61] neg_lo:[1,0,0] neg_hi:[1,0,0]
	v_add_f32_e32 v178, v176, v177
	v_pk_fma_f32 v[182:183], v[58:59], v[114:115], v[58:59] neg_lo:[1,0,0] neg_hi:[1,0,0]
	ds_read_b128 v[102:105], v78 offset:23808
	v_add_f32_dpp v178, v178, v178 quad_perm:[1,0,3,2] row_mask:0xf bank_mask:0xf bound_ctrl:1
	v_pk_fma_f32 v[180:181], v[132:133], v[124:125], v[180:181] op_sel_hi:[0,1,1]
	v_pk_fma_f32 v[182:183], v[132:133], v[126:127], v[182:183] op_sel_hi:[0,1,1]
	v_add_f32_dpp v178, v178, v178 quad_perm:[2,3,0,1] row_mask:0xf bank_mask:0xf bound_ctrl:1
	v_pk_mul_f32 v[184:185], v[60:61], v[106:107]
	v_pk_fma_f32 v[184:185], v[58:59], v[108:109], v[184:185]
	v_add_f32_dpp v178, v178, v178 row_half_mirror row_mask:0xf bank_mask:0xf bound_ctrl:1
	v_add_f32_e32 v172, v184, v185
	ds_read_b32 v110, v79 offset:24320
	v_add_f32_dpp v178, v178, v178 row_mirror row_mask:0xf bank_mask:0xf bound_ctrl:1
	ds_read_b128 v[98:101], v78 offset:23552
	ds_read_b128 v[106:109], v78 offset:24064
	v_pk_fma_f32 v[60:61], v[178:179], v[120:121], v[180:181] op_sel_hi:[0,1,1] neg_lo:[1,0,0] neg_hi:[1,0,0]
	v_pk_fma_f32 v[58:59], v[178:179], v[122:123], v[182:183] op_sel_hi:[0,1,1] neg_lo:[1,0,0] neg_hi:[1,0,0]
	s_waitcnt lgkmcnt(7)
; __device__ __forceinline__ bf16_t f2bf(float f) { return (bf16_t)(pack2(f, 0.f) & 0xffffu); }
; __device__ __forceinline__ void rwkv_scan_unit(CP p, int u, char* smem) {
;     ...
;       float d = s0 * kk.x + s1 * kk.y + s2 * kk.z + s3 * kk.w;
;       d = allreduce16(d);
;       const float sa = -d;
;       s0 = fmaf(-s0, om.x, s0); s1 = fmaf(-s1, om.y, s1); s2 = fmaf(-s2, om.z, s2); s3 = fmaf(-s3, om.w, s3);
;       s0 = fmaf(sa, bb.x, s0); s1 = fmaf(sa, bb.y, s1); s2 = fmaf(sa, bb.z, s2); s3 = fmaf(sa, bb.w, s3);
;       s0 = fmaf(vv, kp.x, s0); s1 = fmaf(vv, kp.y, s1); s2 = fmaf(vv, kp.z, s2); s3 = fmaf(vv, kp.w, s3);
;       float y = s0 * rr.x + s1 * rr.y + s2 * rr.z + s3 * rr.w;
;       y = allreduce16(y);
;       if (j == s) ykeep = y;
;       om = om_n; kk = kk_n; bb = bb_n; kp = kp_n; rr = rr_n; vv = vv_n;
;     }
;     Y[(size_t)(rowof(b, c * 16) + j) * 1024 + 256 + h * 64 + rowv] = f2bf(ykeep);
;     if (c + 1 < NCH) lwrite((c + 1) & 1);
;     half_barrier(smem);
	v_pk_mul_f32 v[176:177], v[60:61], v[138:139]
	v_pk_fma_f32 v[176:177], v[58:59], v[140:141], v[176:177]
	v_pk_fma_f32 v[180:181], v[60:61], v[134:135], v[60:61] neg_lo:[1,0,0] neg_hi:[1,0,0]
	v_add_f32_e32 v178, v176, v177
	v_pk_fma_f32 v[182:183], v[58:59], v[136:137], v[58:59] neg_lo:[1,0,0] neg_hi:[1,0,0]
	s_nop 0
	v_add_f32_dpp v178, v178, v178 quad_perm:[1,0,3,2] row_mask:0xf bank_mask:0xf bound_ctrl:1
	v_pk_fma_f32 v[180:181], v[146:147], v[152:153], v[180:181] op_sel_hi:[0,1,1]
	v_pk_fma_f32 v[182:183], v[146:147], v[154:155], v[182:183] op_sel_hi:[0,1,1]
	v_add_f32_dpp v178, v178, v178 quad_perm:[2,3,0,1] row_mask:0xf bank_mask:0xf bound_ctrl:1
	v_pk_mul_f32 v[184:185], v[60:61], v[128:129]
	v_pk_fma_f32 v[184:185], v[58:59], v[130:131], v[184:185]
	v_add_f32_dpp v178, v178, v178 row_half_mirror row_mask:0xf bank_mask:0xf bound_ctrl:1
	v_add_f32_e32 v173, v184, v185
	s_nop 0
	v_add_f32_dpp v178, v178, v178 row_mirror row_mask:0xf bank_mask:0xf bound_ctrl:1
	v_pk_fma_f32 v[60:61], v[178:179], v[142:143], v[180:181] op_sel_hi:[0,1,1] neg_lo:[1,0,0] neg_hi:[1,0,0]
	v_pk_fma_f32 v[58:59], v[178:179], v[144:145], v[182:183] op_sel_hi:[0,1,1] neg_lo:[1,0,0] neg_hi:[1,0,0]
	s_waitcnt lgkmcnt(1)
	v_pk_mul_f32 v[176:177], v[60:61], v[94:95]
	v_pk_fma_f32 v[176:177], v[58:59], v[96:97], v[176:177]
	v_pk_fma_f32 v[180:181], v[60:61], v[90:91], v[60:61] neg_lo:[1,0,0] neg_hi:[1,0,0]
	v_add_f32_e32 v178, v176, v177
	v_pk_fma_f32 v[182:183], v[58:59], v[92:93], v[58:59] neg_lo:[1,0,0] neg_hi:[1,0,0]
	s_nop 0
	v_add_f32_dpp v178, v178, v178 quad_perm:[1,0,3,2] row_mask:0xf bank_mask:0xf bound_ctrl:1
	v_pk_fma_f32 v[180:181], v[110:111], v[102:103], v[180:181] op_sel_hi:[0,1,1]
	v_pk_fma_f32 v[182:183], v[110:111], v[104:105], v[182:183] op_sel_hi:[0,1,1]
	v_add_f32_dpp v178, v178, v178 quad_perm:[2,3,0,1] row_mask:0xf bank_mask:0xf bound_ctrl:1
	v_pk_mul_f32 v[184:185], v[60:61], v[156:157]
	v_pk_fma_f32 v[184:185], v[58:59], v[158:159], v[184:185]
	v_add_f32_dpp v178, v178, v178 row_half_mirror row_mask:0xf bank_mask:0xf bound_ctrl:1
	v_add_f32_e32 v174, v184, v185
	s_nop 0
	v_add_f32_dpp v178, v178, v178 row_mirror row_mask:0xf bank_mask:0xf bound_ctrl:1
	v_pk_fma_f32 v[60:61], v[178:179], v[98:99], v[180:181] op_sel_hi:[0,1,1] neg_lo:[1,0,0] neg_hi:[1,0,0]
	v_pk_fma_f32 v[58:59], v[178:179], v[100:101], v[182:183] op_sel_hi:[0,1,1] neg_lo:[1,0,0] neg_hi:[1,0,0]
	s_waitcnt lgkmcnt(0)
	v_pk_mul_f32 v[184:185], v[60:61], v[106:107]
	v_pk_fma_f32 v[184:185], v[58:59], v[108:109], v[184:185]
	v_add_f32_e32 v175, v184, v185
	v_add_f32_dpp v160, v160, v160 row_ror:8 row_mask:0xf bank_mask:0x3 bound_ctrl:1
	v_add_f32_dpp v161, v161, v161 row_ror:8 row_mask:0xf bank_mask:0x3 bound_ctrl:1
	v_add_f32_dpp v162, v162, v162 row_ror:8 row_mask:0xf bank_mask:0x3 bound_ctrl:1
	v_add_f32_dpp v163, v163, v163 row_ror:8 row_mask:0xf bank_mask:0x3 bound_ctrl:1
	v_add_f32_dpp v164, v164, v164 row_ror:8 row_mask:0xf bank_mask:0x3 bound_ctrl:1
	v_add_f32_dpp v165, v165, v165 row_ror:8 row_mask:0xf bank_mask:0x3 bound_ctrl:1
	v_add_f32_dpp v166, v166, v166 row_ror:8 row_mask:0xf bank_mask:0x3 bound_ctrl:1
	v_add_f32_dpp v167, v167, v167 row_ror:8 row_mask:0xf bank_mask:0x3 bound_ctrl:1
	v_add_f32_dpp v160, v168, v168 row_ror:8 row_mask:0xf bank_mask:0xc bound_ctrl:1
	v_add_f32_dpp v161, v169, v169 row_ror:8 row_mask:0xf bank_mask:0xc bound_ctrl:1
	v_add_f32_dpp v162, v170, v170 row_ror:8 row_mask:0xf bank_mask:0xc bound_ctrl:1
	v_add_f32_dpp v163, v171, v171 row_ror:8 row_mask:0xf bank_mask:0xc bound_ctrl:1
	v_add_f32_dpp v164, v172, v172 row_ror:8 row_mask:0xf bank_mask:0xc bound_ctrl:1
	v_add_f32_dpp v165, v173, v173 row_ror:8 row_mask:0xf bank_mask:0xc bound_ctrl:1
	v_add_f32_dpp v166, v174, v174 row_ror:8 row_mask:0xf bank_mask:0xc bound_ctrl:1
	v_add_f32_dpp v167, v175, v175 row_ror:8 row_mask:0xf bank_mask:0xc bound_ctrl:1
	v_add_f32_dpp v160, v160, v160 row_half_mirror row_mask:0xf bank_mask:0x5 bound_ctrl:1
	v_add_f32_dpp v161, v161, v161 row_half_mirror row_mask:0xf bank_mask:0x5 bound_ctrl:1
	v_add_f32_dpp v162, v162, v162 row_half_mirror row_mask:0xf bank_mask:0x5 bound_ctrl:1
	v_add_f32_dpp v163, v163, v163 row_half_mirror row_mask:0xf bank_mask:0x5 bound_ctrl:1
	v_add_f32_dpp v160, v164, v164 row_half_mirror row_mask:0xf bank_mask:0xa bound_ctrl:1
	v_add_f32_dpp v161, v165, v165 row_half_mirror row_mask:0xf bank_mask:0xa bound_ctrl:1
	v_add_f32_dpp v162, v166, v166 row_half_mirror row_mask:0xf bank_mask:0xa bound_ctrl:1
	v_add_f32_dpp v163, v167, v167 row_half_mirror row_mask:0xf bank_mask:0xa bound_ctrl:1
	v_and_b32_e32 v186, 2, v76
	v_cmp_ne_u32_e32 vcc, 0, v186
	v_and_b32_e32 v186, 1, v76
	s_nop 0
	v_cndmask_b32_e32 v187, v160, v162, vcc
	v_cndmask_b32_e32 v188, v162, v160, vcc
	v_cndmask_b32_e32 v189, v161, v163, vcc
	v_cndmask_b32_e32 v190, v163, v161, vcc
	v_cmp_ne_u32_e32 vcc, 0, v186
	v_add_f32_dpp v160, v188, v187 quad_perm:[2,3,0,1] row_mask:0xf bank_mask:0xf bound_ctrl:1
	v_add_f32_dpp v161, v190, v189 quad_perm:[2,3,0,1] row_mask:0xf bank_mask:0xf bound_ctrl:1
	v_cndmask_b32_e32 v187, v160, v161, vcc
	v_cndmask_b32_e32 v188, v161, v160, vcc
	s_nop 1
	v_add_f32_dpp v82, v188, v187 quad_perm:[1,0,3,2] row_mask:0xf bank_mask:0xf bound_ctrl:1
	s_lshl_b32 s5, s4, 4
	s_add_i32 s5, s5, s11
	s_cmp_eq_u32 s4, 0
	s_cselect_b32 s5, s10, s5
	v_or_b32_e32 v12, s5, v76
	v_ashrrev_i32_e32 v13, 31, v12
	v_lshlrev_b64 v[12:13], 11, v[12:13]
	v_cvt_pk_bf16_f32 v14, v82, s0
	v_lshl_add_u64 v[12:13], v[56:57], 0, v[12:13]
	global_store_short v[12:13], v14, off
	s_waitcnt lgkmcnt(0)
	s_mov_b64 s[12:13], exec
	s_mov_b64 exec, 1
	ds_add_u32 v193, v195 offset:8
	s_mov_b64 exec, s[12:13]
	v_add_u32_e32 v194, 4, v194

; __device__ __forceinline__ void run_phase(CP p, int ph, char* smem_full) {
;     ...
;       for (int u = vb; u < 320; u += NVB) {
;         if (u < 128) { for (int rr_ = 0; rr_ < ((SCAN_REP >> 0) & 1) + 1; ++rr_) rwkv_scan_unit(p, u, smem); }
;         else if (u < 256) { for (int rr_ = 0; rr_ < ((SCAN_REP >> 1) & 1) + 1; ++rr_) ssd_scan_unit(p, l, u - 128, smem); }
;         else if (u < 272) ret_mfma_unit(p, l, u - 256, smem);
;         else if (u < 288) { }
;         else if (u < 320) { for (int rr_ = 0; rr_ < ((SCAN_REP >> 3) & 1) + 1; ++rr_) lru_scan_unit(p, u - 288, smem); }
;       }
;       {
;         const int nwork = NVB > 320 ? NVB - 320 : NVB;
;         const int wk = NVB > 320 ? vb - 320 : vb;
;         const int ngu = 16 * 44;
;         if (wk >= 0) {
;           for (int id = wk; id < 256 + 2 * ngu + 44 * 16; id += nwork) {
;             if (id < 256) conv_tile(p.in[7] + (size_t)l * D * D, WO, D, D, (id % 16) * 64, (id / 16) * 64, 0, smem);
;             else if (id < 256 + ngu) { const int k = id - 256; conv_tile(p.in[33] + (size_t)l * D * DFF, WA, D, DFF, (k % 16) * 64, (k / 16) * 64, 1, smem); }
;             else if (id < 256 + 2 * ngu) { const int k = id - 256 - ngu; conv_tile(p.in[34] + (size_t)l * D * DFF, WA, D, DFF, (k % 16) * 64, (k / 16) * 64, 2, smem); }
;             else { const int k = id - 256 - 2 * ngu; conv_tile(p.in[35] + (size_t)l * DFF * D, WB, DFF, D, (k % 44) * 64, (k / 44) * 64, 0, smem); }
;           }
.Lrw_bdoneO:
	s_mov_b32 s4, s28
	s_cmpk_lt_i32 s28, 0x81
	s_cbranch_scc1 .Lrw_headE
.Lrw_exit:
	s_branch .LBB0_394
.LBB0_586:
	v_readlane_b32 s2, v253, 2
	s_add_i32 s4, s54, 0xfffffec0
	v_readlane_b32 s3, v253, 3
	s_and_b64 s[2:3], s[2:3], exec
	s_cselect_b32 s10, s4, s54
	s_cmpk_gt_u32 s10, 0x93f
	s_mov_b32 s37, 0x10000
	s_cbranch_scc1 .LBB0_649
	v_readlane_b32 s0, v254, 12
	v_readlane_b32 s1, v254, 13
	s_mul_hi_i32 s11, s0, 0xb00000
	s_mul_i32 s28, s0, 0xb00000
	s_lshl_b64 s[2:3], s[0:1], 22
	v_readlane_b32 s0, v253, 63
	v_readlane_b32 s1, v254, 0
	s_load_dwordx2 s[4:5], s[0:1], 0x118
	s_load_dwordx4 s[12:15], s[0:1], 0x108
	s_waitcnt lgkmcnt(0)
	s_add_u32 s38, s4, s28
	s_addc_u32 s39, s5, s11
	s_load_dwordx2 s[4:5], s[0:1], 0x38
	s_add_u32 s40, s14, s28
	s_addc_u32 s41, s15, s11
	s_add_u32 s42, s12, s28
	s_addc_u32 s43, s13, s11
	s_waitcnt lgkmcnt(0)
	s_add_u32 s44, s4, s2
	s_addc_u32 s45, s5, s3
	s_branch .LBB0_590
